# DA: next-tile LDS write issued under the MFMA drain of the fast path; NSA compressed-branch pass 2: unmasked sub-tiles skip the per-element causal select; win/cmp LDS fragment reads hoisted
# speedup vs baseline: 1.0471x; 1.0123x over previous
; __device__ __forceinline__ int rowi32(int i, int h) { return (i & 3) + 8 * (i >> 2) + 4 * h; }
; __device__ __forceinline__ void attn_fast_x2(float mr1, f32x16& L1, f32x16& oa0, f32x16& oa1, float mr2, f32x16& L2, f32x16& ob0, f32x16& ob1, ...
;     ...
;     if (need_mask) {
; #pragma unroll
;         for (int i = 0; i < 16; ++i) { const bool ok = (key0 + rowi32(i, h)) <= qpos; s1[i] = ok ? s1[i] : NEG; s2[i] = ok ? s2[i] : NEG; }
;     }
; __device__ __forceinline__ void phase_da(const Params& p, int layer, LAS unsigned char* lds, const bf16_t* Z, bf16_t* Mixed, int tid, int wid, int lane) {
;     ...
;                 for (int sub = 0; sub < 2; ++sub) {
;                     const int k0 = 64 * t + 32 * sub;
;                     if (k0 > q0w + 31) continue;
;                     const bool nm = (k0 + 31 > q0w);
;                     if (t == 0 && sub == 0) {
;                         attn_sub_x2(m1, l1, oa0, oa1, m2, l2, ob0, ob1, qf1, qf2, Ks, Vt, 0, k0, qpos, 1.0f, nm, r, h);
;                         l1 += __shfl_xor(l1, 32); l2 += __shfl_xor(l2, 32);
; #pragma unroll
;                         for (int i = 0; i < 16; ++i) { L1[i] = l1; L2[i] = l2; }
;                     } else attn_fast_x2(m1, L1, oa0, oa1, m2, L2, ob0, ob1, qf1, qf2, Ks, Vt, 32 * sub, k0, qpos, nm, r, h);
.LBB0_248:
	s_mov_b32 s29, 0
	s_mul_i32 s18, s20, 0x4800
	s_add_i32 s18, s18, 0
	s_add_i32 s22, s23, 64
	v_add_u32_e32 v181, s18, v253
	s_add_i32 s24, s23, 0x7f
	s_cmp_le_i32 s24, s17
	s_cbranch_scc1 .Lda_fast
	s_cmp_gt_i32 s22, s7
	s_cbranch_scc1 .LBB0_252
	v_lshl_add_u32 v189, v248, 1, v181
	ds_read_b128 v[108:111], v189
	ds_read_b128 v[100:103], v189 offset:32
	ds_read_b128 v[182:185], v189 offset:64
	ds_read_b128 v[104:107], v189 offset:96
	s_add_i32 s24, s23, 0x5f
	s_cmp_le_i32 s24, s17
	s_waitcnt lgkmcnt(3)
	v_mfma_f32_32x32x16_bf16 v[116:131], v[108:111], v[152:155], v[206:221]
	s_waitcnt lgkmcnt(2)
	v_mfma_f32_32x32x16_bf16 v[116:131], v[100:103], v[156:159], v[116:131]
	s_waitcnt lgkmcnt(1)
	v_mfma_f32_32x32x16_bf16 v[132:147], v[182:185], v[160:163], v[190:205]
	s_waitcnt lgkmcnt(0)
	v_mfma_f32_32x32x16_bf16 v[132:147], v[104:107], v[148:151], v[132:147]
	s_cbranch_scc1 .LBB0_251
	v_add_u32_e32 v99, s23, v186
	v_add_u32_e32 v100, 64, v99
	v_cmp_gt_i32_e32 vcc, v100, v230
	s_nop 3
	v_cndmask_b32_e32 v116, v116, v180, vcc
	s_nop 4
	v_cndmask_b32_e32 v132, v132, v180, vcc
	v_cmp_lt_i32_e32 vcc, v100, v230
	v_add_u32_e32 v100, 0x42, v99
	s_nop 0
	v_cndmask_b32_e32 v117, v180, v117, vcc
	v_cndmask_b32_e32 v133, v180, v133, vcc
	v_cmp_gt_i32_e32 vcc, v100, v230
	v_add_u32_e32 v100, 0x43, v99
	s_nop 0
	v_cndmask_b32_e32 v118, v118, v180, vcc
	v_cndmask_b32_e32 v134, v134, v180, vcc
	v_cmp_gt_i32_e32 vcc, v100, v230
	v_add_u32_e32 v100, 0x48, v99
	s_nop 0
	v_cndmask_b32_e32 v119, v119, v180, vcc
	v_cndmask_b32_e32 v135, v135, v180, vcc
	v_cmp_gt_i32_e32 vcc, v100, v230
	v_add_u32_e32 v100, 0x49, v99
	s_nop 0
	v_cndmask_b32_e32 v120, v120, v180, vcc
	v_cndmask_b32_e32 v136, v136, v180, vcc
	v_cmp_gt_i32_e32 vcc, v100, v230
	v_add_u32_e32 v100, 0x4a, v99
	s_nop 0
	v_cndmask_b32_e32 v121, v121, v180, vcc
	v_cndmask_b32_e32 v137, v137, v180, vcc
	v_cmp_gt_i32_e32 vcc, v100, v230
	v_add_u32_e32 v100, 0x4b, v99
	s_nop 0
	v_cndmask_b32_e32 v122, v122, v180, vcc
	v_cndmask_b32_e32 v138, v138, v180, vcc
	v_cmp_gt_i32_e32 vcc, v100, v230
	v_add_u32_e32 v100, 0x50, v99
	s_nop 0
	v_cndmask_b32_e32 v123, v123, v180, vcc
	v_cndmask_b32_e32 v139, v139, v180, vcc
	v_cmp_gt_i32_e32 vcc, v100, v230
	v_add_u32_e32 v100, 0x51, v99
	s_nop 0
	v_cndmask_b32_e32 v124, v124, v180, vcc
	v_cndmask_b32_e32 v140, v140, v180, vcc
	v_cmp_gt_i32_e32 vcc, v100, v230
	v_add_u32_e32 v100, 0x52, v99
	s_nop 0
	v_cndmask_b32_e32 v125, v125, v180, vcc
	v_cndmask_b32_e32 v141, v141, v180, vcc
	v_cmp_gt_i32_e32 vcc, v100, v230
	v_add_u32_e32 v100, 0x53, v99
	s_nop 0
	v_cndmask_b32_e32 v126, v126, v180, vcc
	v_cndmask_b32_e32 v142, v142, v180, vcc
	v_cmp_gt_i32_e32 vcc, v100, v230
	v_add_u32_e32 v100, 0x58, v99
	s_nop 0
	v_cndmask_b32_e32 v127, v127, v180, vcc
	v_cndmask_b32_e32 v143, v143, v180, vcc
	v_cmp_gt_i32_e32 vcc, v100, v230
	v_add_u32_e32 v100, 0x59, v99
	s_nop 0
	v_cndmask_b32_e32 v128, v128, v180, vcc
	v_cndmask_b32_e32 v144, v144, v180, vcc
	v_cmp_gt_i32_e32 vcc, v100, v230
	v_add_u32_e32 v100, 0x5a, v99
	v_add_u32_e32 v99, 0x5b, v99
	v_cndmask_b32_e32 v129, v129, v180, vcc
	v_cndmask_b32_e32 v145, v145, v180, vcc
	v_cmp_gt_i32_e32 vcc, v100, v230
	s_nop 1
	v_cndmask_b32_e32 v130, v130, v180, vcc
	v_cndmask_b32_e32 v146, v146, v180, vcc
	v_cmp_gt_i32_e32 vcc, v99, v230
	s_nop 1
	v_cndmask_b32_e32 v131, v131, v180, vcc
	v_cndmask_b32_e32 v147, v147, v180, vcc

; __device__ __forceinline__ void phase_da(const Params& p, int layer, LAS unsigned char* lds, const bf16_t* Z, bf16_t* Mixed, int tid, int wid, int lane) {
;     ...
;                 if (__any((L1[0] > 1e30f) | (L2[0] > 1e30f))) {
;                     m1 += 100.f; m2 += 100.f; const float dn = 7.888609052210118e-31f;
; #pragma unroll
;                     for (int i = 0; i < 16; ++i) { oa0[i] *= dn; oa1[i] *= dn; ob0[i] *= dn; ob1[i] *= dn; L1[i] *= dn; L2[i] *= dn; }
;                 }
.Lda_guard_body:
	v_pk_mul_f32 v[48:49], v[48:49], s[56:57] op_sel_hi:[1,0]
	v_pk_mul_f32 v[46:47], v[46:47], s[56:57] op_sel_hi:[1,0]
	v_pk_mul_f32 v[44:45], v[44:45], s[56:57] op_sel_hi:[1,0]
	v_pk_mul_f32 v[42:43], v[42:43], s[56:57] op_sel_hi:[1,0]
	v_pk_mul_f32 v[40:41], v[40:41], s[56:57] op_sel_hi:[1,0]
	v_pk_mul_f32 v[38:39], v[38:39], s[56:57] op_sel_hi:[1,0]
	v_pk_mul_f32 v[36:37], v[36:37], s[56:57] op_sel_hi:[1,0]
	v_pk_mul_f32 v[34:35], v[34:35], s[56:57] op_sel_hi:[1,0]
	v_pk_mul_f32 v[80:81], v[80:81], s[56:57] op_sel_hi:[1,0]
	v_pk_mul_f32 v[78:79], v[78:79], s[56:57] op_sel_hi:[1,0]
	v_pk_mul_f32 v[76:77], v[76:77], s[56:57] op_sel_hi:[1,0]
	v_pk_mul_f32 v[74:75], v[74:75], s[56:57] op_sel_hi:[1,0]
	v_pk_mul_f32 v[72:73], v[72:73], s[56:57] op_sel_hi:[1,0]
	v_pk_mul_f32 v[70:71], v[70:71], s[56:57] op_sel_hi:[1,0]
	v_pk_mul_f32 v[68:69], v[68:69], s[56:57] op_sel_hi:[1,0]
	v_pk_mul_f32 v[66:67], v[66:67], s[56:57] op_sel_hi:[1,0]
	v_pk_mul_f32 v[96:97], v[96:97], s[56:57] op_sel_hi:[1,0]
	v_pk_mul_f32 v[94:95], v[94:95], s[56:57] op_sel_hi:[1,0]
	v_pk_mul_f32 v[92:93], v[92:93], s[56:57] op_sel_hi:[1,0]
	v_pk_mul_f32 v[90:91], v[90:91], s[56:57] op_sel_hi:[1,0]
	v_pk_mul_f32 v[88:89], v[88:89], s[56:57] op_sel_hi:[1,0]
	v_pk_mul_f32 v[86:87], v[86:87], s[56:57] op_sel_hi:[1,0]
	v_pk_mul_f32 v[84:85], v[84:85], s[56:57] op_sel_hi:[1,0]
	v_pk_mul_f32 v[82:83], v[82:83], s[56:57] op_sel_hi:[1,0]
	v_pk_mul_f32 v[64:65], v[64:65], s[56:57] op_sel_hi:[1,0]
	v_pk_mul_f32 v[62:63], v[62:63], s[56:57] op_sel_hi:[1,0]
	v_pk_mul_f32 v[60:61], v[60:61], s[56:57] op_sel_hi:[1,0]
	v_pk_mul_f32 v[58:59], v[58:59], s[56:57] op_sel_hi:[1,0]
	v_pk_mul_f32 v[56:57], v[56:57], s[56:57] op_sel_hi:[1,0]
	v_pk_mul_f32 v[54:55], v[54:55], s[56:57] op_sel_hi:[1,0]
	v_pk_mul_f32 v[52:53], v[52:53], s[56:57] op_sel_hi:[1,0]
	v_pk_mul_f32 v[50:51], v[50:51], s[56:57] op_sel_hi:[1,0]
	v_pk_mul_f32 v[16:17], v[16:17], s[56:57] op_sel_hi:[1,0]
	v_pk_mul_f32 v[14:15], v[14:15], s[56:57] op_sel_hi:[1,0]
	v_pk_mul_f32 v[12:13], v[12:13], s[56:57] op_sel_hi:[1,0]
	v_pk_mul_f32 v[10:11], v[10:11], s[56:57] op_sel_hi:[1,0]
	v_pk_mul_f32 v[8:9], v[8:9], s[56:57] op_sel_hi:[1,0]
	v_pk_mul_f32 v[6:7], v[6:7], s[56:57] op_sel_hi:[1,0]
	v_pk_mul_f32 v[4:5], v[4:5], s[56:57] op_sel_hi:[1,0]
	v_pk_mul_f32 v[2:3], v[2:3], s[56:57] op_sel_hi:[1,0]
	v_pk_mul_f32 v[32:33], v[32:33], s[56:57] op_sel_hi:[1,0]
	v_pk_mul_f32 v[30:31], v[30:31], s[56:57] op_sel_hi:[1,0]
	v_pk_mul_f32 v[28:29], v[28:29], s[56:57] op_sel_hi:[1,0]
	v_pk_mul_f32 v[26:27], v[26:27], s[56:57] op_sel_hi:[1,0]
	v_pk_mul_f32 v[24:25], v[24:25], s[56:57] op_sel_hi:[1,0]
	v_pk_mul_f32 v[22:23], v[22:23], s[56:57] op_sel_hi:[1,0]
	v_pk_mul_f32 v[20:21], v[20:21], s[56:57] op_sel_hi:[1,0]
	v_pk_mul_f32 v[18:19], v[18:19], s[56:57] op_sel_hi:[1,0]
	v_pk_add_f32 v[232:233], v[232:233], s[58:59] op_sel_hi:[1,0]
	v_xor_b32_e32 v206, 0x80000000, v232
	v_xor_b32_e32 v190, 0x80000000, v233
	v_mov_b32_e32 v207, v206
	v_mov_b32_e32 v208, v206
	v_mov_b32_e32 v209, v206
	v_mov_b32_e32 v210, v206
	v_mov_b32_e32 v211, v206
	v_mov_b32_e32 v212, v206
	v_mov_b32_e32 v213, v206
	v_mov_b32_e32 v214, v206
	v_mov_b32_e32 v215, v206
	v_mov_b32_e32 v216, v206
	v_mov_b32_e32 v217, v206
	v_mov_b32_e32 v218, v206
	v_mov_b32_e32 v219, v206
	v_mov_b32_e32 v220, v206
	v_mov_b32_e32 v221, v206
	v_mov_b32_e32 v191, v190
	v_mov_b32_e32 v192, v190
	v_mov_b32_e32 v193, v190
	v_mov_b32_e32 v194, v190
	v_mov_b32_e32 v195, v190
	v_mov_b32_e32 v196, v190
	v_mov_b32_e32 v197, v190
	v_mov_b32_e32 v198, v190
	v_mov_b32_e32 v199, v190
	v_mov_b32_e32 v200, v190
	v_mov_b32_e32 v201, v190
	v_mov_b32_e32 v202, v190
	v_mov_b32_e32 v203, v190
	v_mov_b32_e32 v204, v190
	v_mov_b32_e32 v205, v190
	s_cmp_lg_u32 s29, 0
	s_cbranch_scc1 .Lda_fast_noguard

; #define LAS __attribute__((address_space(3)))
; __device__ __forceinline__ void attn_fast_x2(float mr1, f32x16& L1, f32x16& oa0, f32x16& oa1, float mr2, f32x16& L2, f32x16& ob0, f32x16& ob1, ...
;     ...
;     for (int s2i = 0; s2i < 2; ++s2i) {
;         const bf16x8 pb1 = pack8(p1[8 * s2i + 0], p1[8 * s2i + 1], p1[8 * s2i + 2], p1[8 * s2i + 3], p1[8 * s2i + 4], p1[8 * s2i + 5], p1[8 * s2i + 6], p1[8 * s2i + 7]);
;         const bf16x8 pb2 = pack8(p2[8 * s2i + 0], p2[8 * s2i + 1], p2[8 * s2i + 2], p2[8 * s2i + 3], p2[8 * s2i + 4], p2[8 * s2i + 5], p2[8 * s2i + 6], p2[8 * s2i + 7]);
;         const LAS bf16_t* vp = Vt + r * VP + kr0 + 16 * s2i + 4 * h;
;         const u32x2 a0l = *(const LAS u32x2*)vp, a0h = *(const LAS u32x2*)(vp + 8);
;         const u32x2 a1l = *(const LAS u32x2*)(vp + 32 * VP), a1h = *(const LAS u32x2*)(vp + 32 * VP + 8);
;         const u32x4 v0 = {a0l.x, a0l.y, a0h.x, a0h.y}, v1 = {a1l.x, a1l.y, a1h.x, a1h.y};
;         oa0 = __builtin_amdgcn_mfma_f32_32x32x16_bf16(__builtin_bit_cast(bf16x8, v0), pb1, oa0, 0, 0, 0);
;         ob0 = __builtin_amdgcn_mfma_f32_32x32x16_bf16(__builtin_bit_cast(bf16x8, v0), pb2, ob0, 0, 0, 0);
;         oa1 = __builtin_amdgcn_mfma_f32_32x32x16_bf16(__builtin_bit_cast(bf16x8, v1), pb1, oa1, 0, 0, 0);
;         ob1 = __builtin_amdgcn_mfma_f32_32x32x16_bf16(__builtin_bit_cast(bf16x8, v1), pb2, ob1, 0, 0, 0);
;         L1 = __builtin_amdgcn_mfma_f32_32x32x16_bf16(ones, pb1, L1, 0, 0, 0);
;         L2 = __builtin_amdgcn_mfma_f32_32x32x16_bf16(ones, pb2, L2, 0, 0, 0);
;     }
; }
.Lda_fast:
	v_lshl_add_u32 v189, v248, 1, v181
	v_lshlrev_b32_e32 v99, 1, v248
	v_add3_u32 v99, s18, v240, v99
	ds_read_b128 v[100:103], v189
	ds_read_b128 v[104:107], v189 offset:32
	ds_read_b128 v[108:111], v189 offset:64
	ds_read_b128 v[112:115], v189 offset:96
	ds_read_b128 v[182:185], v99
	ds_read_b128 v[226:229], v99 offset:32
	ds_read_b128 v[242:245], v99 offset:64
	ds_read_b128 v[172:175], v99 offset:96
	v_add_u32_e32 v98, v181, v248
	v_add_u32_e32 v181, 0x3000, v98
	v_add_u32_e32 v98, 0x2000, v98
	s_waitcnt lgkmcnt(7)
	v_mfma_f32_32x32x16_bf16 v[116:131], v[100:103], v[152:155], v[206:221]
	s_waitcnt lgkmcnt(6)
	v_mfma_f32_32x32x16_bf16 v[116:131], v[104:107], v[156:159], v[116:131]
	s_waitcnt lgkmcnt(5)
	v_mfma_f32_32x32x16_bf16 v[132:147], v[108:111], v[160:163], v[190:205]
	s_waitcnt lgkmcnt(4)
	v_mfma_f32_32x32x16_bf16 v[132:147], v[112:115], v[148:151], v[132:147]
	ds_read2_b64 v[100:103], v98 offset0:128 offset1:130
	ds_read2_b64 v[104:107], v181 offset0:192 offset1:194
	ds_read2_b64 v[108:111], v98 offset0:132 offset1:134
	ds_read2_b64 v[112:115], v181 offset0:196 offset1:198
	s_nop 3
	v_exp_f32_e32 v116, v116
	v_exp_f32_e32 v117, v117
	v_exp_f32_e32 v118, v118
	v_exp_f32_e32 v119, v119
	v_exp_f32_e32 v120, v120
	v_exp_f32_e32 v121, v121
	v_exp_f32_e32 v122, v122
	v_exp_f32_e32 v123, v123
	v_cvt_pk_bf16_f32 v116, v116, v117
	v_cvt_pk_bf16_f32 v117, v118, v119
	v_cvt_pk_bf16_f32 v118, v120, v121
	v_cvt_pk_bf16_f32 v119, v122, v123
	s_waitcnt lgkmcnt(2)
	s_nop 0
	v_mfma_f32_32x32x16_bf16 v[34:49], v[100:103], v[116:119], v[34:49]
	v_exp_f32_e32 v124, v124
	v_exp_f32_e32 v125, v125
	v_exp_f32_e32 v126, v126
	v_mfma_f32_32x32x16_bf16 v[66:81], v[104:107], v[116:119], v[66:81]
	v_exp_f32_e32 v127, v127
	v_exp_f32_e32 v128, v128
	v_exp_f32_e32 v129, v129
	v_mfma_f32_32x32x16_bf16 v[2:17], v[222:225], v[116:119], v[2:17]
	v_exp_f32_e32 v130, v130
	v_exp_f32_e32 v131, v131
	v_cvt_pk_bf16_f32 v120, v124, v125
	v_cvt_pk_bf16_f32 v121, v126, v127
	v_cvt_pk_bf16_f32 v122, v128, v129
	v_cvt_pk_bf16_f32 v123, v130, v131
	s_waitcnt lgkmcnt(0)
	s_nop 0
	v_mfma_f32_32x32x16_bf16 v[34:49], v[108:111], v[120:123], v[34:49]
	v_exp_f32_e32 v132, v132
	v_exp_f32_e32 v133, v133
	v_exp_f32_e32 v134, v134
	v_mfma_f32_32x32x16_bf16 v[66:81], v[112:115], v[120:123], v[66:81]
	v_exp_f32_e32 v135, v135
	v_exp_f32_e32 v136, v136
	v_exp_f32_e32 v137, v137
	v_mfma_f32_32x32x16_bf16 v[2:17], v[222:225], v[120:123], v[2:17]
	v_exp_f32_e32 v138, v138
	v_exp_f32_e32 v139, v139
	v_cvt_pk_bf16_f32 v132, v132, v133
	v_cvt_pk_bf16_f32 v133, v134, v135
	v_mfma_f32_32x32x16_bf16 v[116:131], v[182:185], v[152:155], v[206:221]
	v_cvt_pk_bf16_f32 v134, v136, v137
	v_cvt_pk_bf16_f32 v135, v138, v139
	v_exp_f32_e32 v140, v140
	v_exp_f32_e32 v141, v141
	v_mfma_f32_32x32x16_bf16 v[116:131], v[226:229], v[156:159], v[116:131]
	v_exp_f32_e32 v142, v142
	v_exp_f32_e32 v143, v143
	v_exp_f32_e32 v144, v144
	ds_read2_b64 v[182:185], v98 offset0:136 offset1:138
	ds_read2_b64 v[226:229], v181 offset0:200 offset1:202
	v_mfma_f32_32x32x16_bf16 v[82:97], v[100:103], v[132:135], v[82:97]
	v_exp_f32_e32 v145, v145
	v_exp_f32_e32 v146, v146
	v_exp_f32_e32 v147, v147
	v_mfma_f32_32x32x16_bf16 v[50:65], v[104:107], v[132:135], v[50:65]
	v_cvt_pk_bf16_f32 v136, v140, v141
	v_cvt_pk_bf16_f32 v137, v142, v143
	v_cvt_pk_bf16_f32 v138, v144, v145
	v_cvt_pk_bf16_f32 v139, v146, v147
	ds_read2_b64 v[100:103], v98 offset0:140 offset1:142
	ds_read2_b64 v[104:107], v181 offset0:204 offset1:206
	v_mfma_f32_32x32x16_bf16 v[18:33], v[222:225], v[132:135], v[18:33]
	v_exp_f32_e32 v116, v116
	v_exp_f32_e32 v117, v117
	v_exp_f32_e32 v118, v118
	v_mfma_f32_32x32x16_bf16 v[82:97], v[108:111], v[136:139], v[82:97]
	v_exp_f32_e32 v119, v119
	v_exp_f32_e32 v120, v120
	v_exp_f32_e32 v121, v121
	v_mfma_f32_32x32x16_bf16 v[50:65], v[112:115], v[136:139], v[50:65]
	v_exp_f32_e32 v122, v122
	v_exp_f32_e32 v123, v123
	v_cvt_pk_bf16_f32 v116, v116, v117
	v_cvt_pk_bf16_f32 v117, v118, v119
	v_mfma_f32_32x32x16_bf16 v[18:33], v[222:225], v[136:139], v[18:33]
	v_cvt_pk_bf16_f32 v118, v120, v121
	v_cvt_pk_bf16_f32 v119, v122, v123
	v_exp_f32_e32 v124, v124
	v_exp_f32_e32 v125, v125
	v_mfma_f32_32x32x16_bf16 v[132:147], v[242:245], v[160:163], v[190:205]
	v_exp_f32_e32 v126, v126
	v_exp_f32_e32 v127, v127
	v_exp_f32_e32 v128, v128
	v_mfma_f32_32x32x16_bf16 v[132:147], v[172:175], v[148:151], v[132:147]
	v_exp_f32_e32 v129, v129
	v_exp_f32_e32 v130, v130
	v_exp_f32_e32 v131, v131
	s_waitcnt lgkmcnt(2)
	v_mfma_f32_32x32x16_bf16 v[34:49], v[182:185], v[116:119], v[34:49]
	v_cvt_pk_bf16_f32 v120, v124, v125
	v_cvt_pk_bf16_f32 v121, v126, v127
	v_cvt_pk_bf16_f32 v122, v128, v129
	v_cvt_pk_bf16_f32 v123, v130, v131
	v_mfma_f32_32x32x16_bf16 v[66:81], v[226:229], v[116:119], v[66:81]
	s_nop 1
	v_exp_f32_e32 v132, v132
	v_exp_f32_e32 v133, v133
	v_exp_f32_e32 v134, v134
	v_mfma_f32_32x32x16_bf16 v[2:17], v[222:225], v[116:119], v[2:17]
	v_exp_f32_e32 v135, v135
	v_exp_f32_e32 v136, v136
	v_exp_f32_e32 v137, v137
	s_waitcnt lgkmcnt(0)
	v_mfma_f32_32x32x16_bf16 v[34:49], v[100:103], v[120:123], v[34:49]
	v_exp_f32_e32 v138, v138
	v_exp_f32_e32 v139, v139
	v_cvt_pk_bf16_f32 v132, v132, v133
	v_cvt_pk_bf16_f32 v133, v134, v135
	v_mfma_f32_32x32x16_bf16 v[66:81], v[104:107], v[120:123], v[66:81]
	v_cvt_pk_bf16_f32 v134, v136, v137
	v_cvt_pk_bf16_f32 v135, v138, v139
	v_exp_f32_e32 v140, v140
	v_exp_f32_e32 v141, v141
	v_mfma_f32_32x32x16_bf16 v[2:17], v[222:225], v[120:123], v[2:17]
	v_exp_f32_e32 v142, v142
	v_exp_f32_e32 v143, v143
	v_exp_f32_e32 v144, v144
	v_mfma_f32_32x32x16_bf16 v[18:33], v[222:225], v[132:135], v[18:33]
	v_exp_f32_e32 v145, v145
	v_exp_f32_e32 v146, v146
	v_exp_f32_e32 v147, v147
	v_mfma_f32_32x32x16_bf16 v[82:97], v[182:185], v[132:135], v[82:97]
	v_cvt_pk_bf16_f32 v136, v140, v141
	v_cvt_pk_bf16_f32 v137, v142, v143
	v_cvt_pk_bf16_f32 v138, v144, v145
	v_cvt_pk_bf16_f32 v139, v146, v147
	v_mfma_f32_32x32x16_bf16 v[50:65], v[226:229], v[132:135], v[50:65]
	s_nop 0
	v_mfma_f32_32x32x16_bf16 v[18:33], v[222:225], v[136:139], v[18:33]
	v_mfma_f32_32x32x16_bf16 v[82:97], v[100:103], v[136:139], v[82:97]
	v_mfma_f32_32x32x16_bf16 v[50:65], v[104:107], v[136:139], v[50:65]
	s_xor_b32 s24, s20, 1
	s_mul_i32 s24, s24, 0x4800
	v_add3_u32 v189, s24, v249, v238
	s_waitcnt vmcnt(1)
	ds_write_b128 v189, v[168:171]
	v_lshl_add_u32 v189, v251, 1, s24
	s_waitcnt vmcnt(0)
	ds_write_b16 v189, v164 offset:9216
	ds_write_b16_d16_hi v189, v164 offset:9360
	ds_write_b16 v189, v165 offset:9504
	ds_write_b16_d16_hi v189, v165 offset:9648
	ds_write_b16 v189, v166 offset:9792
	ds_write_b16_d16_hi v189, v166 offset:9936
	ds_write_b16 v189, v167 offset:10080
	v_lshl_add_u32 v189, v239, 1, s24
	s_cmp_ge_u32 s21, s6
	ds_write_b16_d16_hi v189, v167 offset:9216
	s_cbranch_scc1 .Lda_fast_nofetch
	global_load_dwordx4 v[168:171], v[234:235], off
	global_load_dwordx4 v[164:167], v[236:237], off
; #define TL_NEXT(Kg, kpitch, Vg, vpitch, t, t1, bi) do { if ((t) + 1 < (t1)) { TL_WRITE((bi) ^ 1); if ((t) + 2 < (t1)) TL_FETCH(Kg, kpitch, Vg, vpitch, (t) + 2); } __syncthreads(); } while (0)
; __device__ __forceinline__ void phase_da(const Params& p, int layer, LAS unsigned char* lds, const bf16_t* Z, bf16_t* Mixed, int tid, int wid, int lane) {
;     ...
;                 if (__any((L1[0] > 1e30f) | (L2[0] > 1e30f))) {
;                     m1 += 100.f; m2 += 100.f; const float dn = 7.888609052210118e-31f;
; #pragma unroll
;                     for (int i = 0; i < 16; ++i) { oa0[i] *= dn; oa1[i] *= dn; ob0[i] *= dn; ob1[i] *= dn; L1[i] *= dn; L2[i] *= dn; }
;                 }
;                 TL_NEXT(Kg, ZLD, Vg, ZLD, t, ntile, bi);
.Lda_fast_nofetch:
	v_max_f32_e32 v98, v18, v18
	v_max_f32_e32 v99, v2, v2
	v_max_f32_e32 v98, v99, v98
	v_cmp_lt_f32_e32 vcc, s33, v98
	s_cbranch_vccz .Lda_fast_noguard
	s_mov_b32 s29, 1
	s_branch .Lda_guard_body
.Lda_fast_noguard:
	s_xor_b32 s20, s20, 1
	s_mul_i32 s23, s20, 0x4800
	s_branch .LBB0_260

; #define LAS __attribute__((address_space(3)))
; __device__ __forceinline__ int rowi32(int i, int h) { return (i & 3) + 8 * (i >> 2) + 4 * h; }
; template <int ND>
; __device__ __forceinline__ f32x16 qk_sub(const bf16x8 (&qf)[ND], const LAS bf16_t* Ks, int kr0, int kc0, int r, int h) {
;     f32x16 s;
; #pragma unroll
;     for (int i = 0; i < 16; ++i) s[i] = 0.f;
; #pragma unroll
;     for (int ks = 0; ks < ND; ++ks) { const bf16x8 a = *(const LAS bf16x8*)(Ks + (kr0 + r) * KP + kc0 + 16 * ks + 8 * h); s = __builtin_amdgcn_mfma_f32_32x32x16_bf16(a, qf[ks], s, 0, 0, 0); }
;     return s;
; }
; template <int MODE> __device__ __forceinline__ bool key_ok(int key, int qpos) {
;     if (MODE == 0) return key <= qpos;
;     if (MODE == 1) return (key <= qpos) && (key > qpos - 512);
;     return 16 * key + 31 <= qpos;
; }
; template <int ND, int MODE>
; __device__ __forceinline__ void attn_sub(float& m, float& l, f32x16& o0, f32x16& o1, const bf16x8 (&qf)[ND], const LAS bf16_t* Ks, const LAS bf16_t* Vt,
;                                          int kr0, int kc0, int key0, int qpos, float c, bool need_mask, int r, int h) {
;     f32x16 s = qk_sub<ND>(qf, Ks, kr0, kc0, r, h);
;     if (need_mask) {
; #pragma unroll
;         for (int i = 0; i < 16; ++i) { const int key = key0 + rowi32(i, h); s[i] = key_ok<MODE>(key, qpos) ? s[i] : NEG; }
;     }
; __device__ __forceinline__ void phase_win(const Params& p, LAS unsigned char* lds, const bf16_t* Z, const float* G, bf16_t* ACCW, int tid, int wid, int lane) {
;     ...
;         for (int t = tlo, bi = 0; t <= qb; ++t, bi ^= 1) {
;             const LAS bf16_t* Ks = Ks0 + bi * TLB; const LAS bf16_t* Vt = Ks + 64 * KP;
; #pragma unroll
;             for (int sub = 0; sub < 2; ++sub) {
;                 const int k0 = 64 * t + 32 * sub;
;                 if (k0 > q0w + 31 || k0 + 31 <= q0w - 512) continue;
;                 const bool nm = !((k0 + 31 <= q0w) && (k0 > q0w + 31 - 512));
;                 attn_sub<4, 1>(m, l, o0, o1, qf, Ks, Vt, 32 * sub, 0, k0, qpos, 1.0f, nm, r, h);
.LBB0_282:
	s_mul_i32 s2, s22, 0x4800
	s_add_i32 s2, s2, 0
	v_add_u32_e32 v107, s2, v99
	s_cmp_gt_i32 s8, s9
	v_add_u32_e32 v106, s2, v100
	s_cbranch_scc1 .LBB0_290
	s_add_i32 s2, s8, 31
	s_cmp_le_i32 s2, s20
	s_cbranch_scc1 .LBB0_290
	v_add_u32_e32 v94, v107, v100
	ds_read_b128 v[34:37], v94
	ds_read_b128 v[108:111], v94 offset:32
	ds_read_b128 v[152:155], v94 offset:64
	ds_read_b128 v[112:115], v94 offset:96
	v_add_u32_e32 v172, v106, v76
	v_add_u32_e32 v173, 0x3000, v172
	v_add_u32_e32 v172, 0x2000, v172
	ds_read2_b64 v[156:159], v172 offset0:128 offset1:130
	ds_read2_b64 v[160:163], v172 offset0:132 offset1:134
	ds_read2_b64 v[164:167], v173 offset0:192 offset1:194
	ds_read2_b64 v[168:171], v173 offset0:196 offset1:198
	s_cmp_gt_i32 s2, s18
	s_cselect_b64 s[2:3], -1, 0
	s_cmp_le_i32 s8, s21
	s_waitcnt lgkmcnt(7)
	v_mfma_f32_32x32x16_bf16 v[34:49], v[34:37], v[58:61], 0
	s_cselect_b64 s[24:25], -1, 0
	s_or_b64 s[2:3], s[2:3], s[24:25]
	s_andn2_b64 vcc, exec, s[2:3]
	s_waitcnt lgkmcnt(6)
	v_mfma_f32_32x32x16_bf16 v[34:49], v[108:111], v[62:65], v[34:49]
	s_waitcnt lgkmcnt(5)
	v_mfma_f32_32x32x16_bf16 v[34:49], v[152:155], v[66:69], v[34:49]
	s_waitcnt lgkmcnt(4)
	v_mfma_f32_32x32x16_bf16 v[34:49], v[112:115], v[70:73], v[34:49]
	s_cbranch_vccnz .LBB0_286
	v_add_u32_e32 v94, s8, v82
	v_cmp_le_i32_e32 vcc, v94, v88
	v_cmp_gt_i32_e64 s[2:3], v94, v105
	s_and_b64 vcc, vcc, s[2:3]
	s_nop 6
	v_cndmask_b32_e32 v34, v180, v34, vcc
	v_cmp_lt_i32_e32 vcc, v94, v88
	v_cmp_ge_i32_e64 s[2:3], v94, v105
	s_and_b64 vcc, vcc, s[2:3]
	v_add_u32_e32 v108, 2, v94
	v_cndmask_b32_e32 v35, v180, v35, vcc
	v_cmp_le_i32_e32 vcc, v108, v88
	v_cmp_gt_i32_e64 s[2:3], v108, v105
	s_and_b64 vcc, vcc, s[2:3]
	v_add_u32_e32 v108, 3, v94
	v_cndmask_b32_e32 v36, v180, v36, vcc
	v_cmp_le_i32_e32 vcc, v108, v88
	v_cmp_gt_i32_e64 s[2:3], v108, v105
	s_and_b64 vcc, vcc, s[2:3]
	v_add_u32_e32 v108, 8, v94
	v_cndmask_b32_e32 v37, v180, v37, vcc
	v_cmp_le_i32_e32 vcc, v108, v88
	v_cmp_gt_i32_e64 s[2:3], v108, v105
	s_and_b64 vcc, vcc, s[2:3]
	v_add_u32_e32 v108, 9, v94
	v_cndmask_b32_e32 v38, v180, v38, vcc
	v_cmp_le_i32_e32 vcc, v108, v88
	v_cmp_gt_i32_e64 s[2:3], v108, v105
	s_and_b64 vcc, vcc, s[2:3]
	v_add_u32_e32 v108, 10, v94
	v_cndmask_b32_e32 v39, v180, v39, vcc
	v_cmp_le_i32_e32 vcc, v108, v88
	v_cmp_gt_i32_e64 s[2:3], v108, v105
	s_and_b64 vcc, vcc, s[2:3]
	v_add_u32_e32 v108, 11, v94
	v_cndmask_b32_e32 v40, v180, v40, vcc
	v_cmp_le_i32_e32 vcc, v108, v88
	v_cmp_gt_i32_e64 s[2:3], v108, v105
	s_and_b64 vcc, vcc, s[2:3]
	v_add_u32_e32 v108, 16, v94
	v_cndmask_b32_e32 v41, v180, v41, vcc
	v_cmp_le_i32_e32 vcc, v108, v88
	v_cmp_gt_i32_e64 s[2:3], v108, v105
	s_and_b64 vcc, vcc, s[2:3]
	v_add_u32_e32 v108, 17, v94
	v_cndmask_b32_e32 v42, v180, v42, vcc
	v_cmp_le_i32_e32 vcc, v108, v88
	v_cmp_gt_i32_e64 s[2:3], v108, v105
	s_and_b64 vcc, vcc, s[2:3]
	v_add_u32_e32 v108, 18, v94
	v_cndmask_b32_e32 v43, v180, v43, vcc
	v_cmp_le_i32_e32 vcc, v108, v88
	v_cmp_gt_i32_e64 s[2:3], v108, v105
	s_and_b64 vcc, vcc, s[2:3]
	v_add_u32_e32 v108, 19, v94
	v_cndmask_b32_e32 v44, v180, v44, vcc
	v_cmp_le_i32_e32 vcc, v108, v88
	v_cmp_gt_i32_e64 s[2:3], v108, v105
	s_and_b64 vcc, vcc, s[2:3]
	v_add_u32_e32 v108, 24, v94
	v_cndmask_b32_e32 v45, v180, v45, vcc
	v_cmp_le_i32_e32 vcc, v108, v88
	v_cmp_gt_i32_e64 s[2:3], v108, v105
	s_and_b64 vcc, vcc, s[2:3]
	v_add_u32_e32 v108, 25, v94
	v_cndmask_b32_e32 v46, v180, v46, vcc
	v_cmp_le_i32_e32 vcc, v108, v88
	v_cmp_gt_i32_e64 s[2:3], v108, v105
	s_and_b64 vcc, vcc, s[2:3]
	v_add_u32_e32 v108, 26, v94
	v_cndmask_b32_e32 v47, v180, v47, vcc
	v_cmp_le_i32_e32 vcc, v108, v88
	v_cmp_gt_i32_e64 s[2:3], v108, v105
	s_and_b64 vcc, vcc, s[2:3]
	v_add_u32_e32 v94, 27, v94
	v_cndmask_b32_e32 v48, v180, v48, vcc
	v_cmp_le_i32_e32 vcc, v94, v88
	v_cmp_gt_i32_e64 s[2:3], v94, v105
	s_and_b64 vcc, vcc, s[2:3]
	v_cndmask_b32_e32 v49, v180, v49, vcc

; #define LAS __attribute__((address_space(3)))
; __device__ __forceinline__ float ex2(float x) { return __builtin_amdgcn_exp2f(x); }
; template <int ND, int MODE>
; __device__ __forceinline__ void attn_sub(float& m, float& l, f32x16& o0, f32x16& o1, const bf16x8 (&qf)[ND], const LAS bf16_t* Ks, const LAS bf16_t* Vt,
;                                          int kr0, int kc0, int key0, int qpos, float c, bool need_mask, int r, int h) {
;     ...
;     float pv[16]; f32x2_t ps2 = {0.f, 0.f}; const f32x2_t c2 = {c, c}, mn2 = {mn, mn};
; #pragma unroll
;     for (int i = 0; i < 8; ++i) { f32x2_t tt = {s[2 * i], s[2 * i + 1]}; tt = (tt - mn2) * c2; pv[2 * i] = ex2(tt.x); pv[2 * i + 1] = ex2(tt.y); const f32x2_t pp = {pv[2 * i], pv[2 * i + 1]}; ps2 += pp; }
;     l = l * alpha + (ps2.x + ps2.y);
; #pragma unroll
;     for (int s2 = 0; s2 < 2; ++s2) {
;         const bf16x8 pb = pack8(pv[8 * s2 + 0], pv[8 * s2 + 1], pv[8 * s2 + 2], pv[8 * s2 + 3], pv[8 * s2 + 4], pv[8 * s2 + 5], pv[8 * s2 + 6], pv[8 * s2 + 7]);
;         const LAS bf16_t* vp = Vt + r * VP + kr0 + 16 * s2 + 4 * h;
;         const u32x2 a0l = *(const LAS u32x2*)vp, a0h = *(const LAS u32x2*)(vp + 8);
;         const u32x2 a1l = *(const LAS u32x2*)(vp + 32 * VP), a1h = *(const LAS u32x2*)(vp + 32 * VP + 8);
;         u32x4 a0 = {a0l.x, a0l.y, a0h.x, a0h.y}, a1 = {a1l.x, a1l.y, a1h.x, a1h.y};
;         o0 = __builtin_amdgcn_mfma_f32_32x32x16_bf16(__builtin_bit_cast(bf16x8, a0), pb, o0, 0, 0, 0);
;         o1 = __builtin_amdgcn_mfma_f32_32x32x16_bf16(__builtin_bit_cast(bf16x8, a1), pb, o1, 0, 0, 0);
;     }
; __device__ __forceinline__ void phase_win(const Params& p, LAS unsigned char* lds, const bf16_t* Z, const float* G, bf16_t* ACCW, int tid, int wid, int lane) {
;     ...
;             for (int sub = 0; sub < 2; ++sub) {
;                 const int k0 = 64 * t + 32 * sub;
;                 if (k0 > q0w + 31 || k0 + 31 <= q0w - 512) continue;
;                 const bool nm = !((k0 + 31 <= q0w) && (k0 > q0w + 31 - 512));
;                 attn_sub<4, 1>(m, l, o0, o1, qf, Ks, Vt, 32 * sub, 0, k0, qpos, 1.0f, nm, r, h);
.LBB0_289:
	v_pk_add_f32 v[34:35], v[34:35], v[94:95] op_sel_hi:[1,0] neg_lo:[0,1] neg_hi:[0,1]
	v_pk_add_f32 v[36:37], v[36:37], v[94:95] op_sel_hi:[1,0] neg_lo:[0,1] neg_hi:[0,1]
	v_exp_f32_e32 v34, v34
	v_exp_f32_e32 v35, v35
	v_exp_f32_e32 v36, v36
	v_exp_f32_e32 v37, v37
	v_pk_add_f32 v[38:39], v[38:39], v[94:95] op_sel_hi:[1,0] neg_lo:[0,1] neg_hi:[0,1]
	v_pk_add_f32 v[40:41], v[40:41], v[94:95] op_sel_hi:[1,0] neg_lo:[0,1] neg_hi:[0,1]
	v_exp_f32_e32 v38, v38
	v_exp_f32_e32 v39, v39
	v_exp_f32_e32 v40, v40
	v_exp_f32_e32 v41, v41
	v_pk_add_f32 v[42:43], v[42:43], v[94:95] op_sel_hi:[1,0] neg_lo:[0,1] neg_hi:[0,1]
	v_pk_add_f32 v[108:109], v[34:35], 0 op_sel_hi:[1,0]
	v_exp_f32_e32 v110, v42
	v_exp_f32_e32 v111, v43
	v_pk_add_f32 v[108:109], v[36:37], v[108:109]
	v_pk_add_f32 v[44:45], v[44:45], v[94:95] op_sel_hi:[1,0] neg_lo:[0,1] neg_hi:[0,1]
	v_pk_add_f32 v[108:109], v[38:39], v[108:109]
	v_cvt_pk_bf16_f32 v34, v34, v35
	v_pk_add_f32 v[108:109], v[40:41], v[108:109]
	v_cvt_pk_bf16_f32 v35, v36, v37
	v_pk_add_f32 v[42:43], v[110:111], v[108:109]
	v_exp_f32_e32 v108, v44
	v_exp_f32_e32 v109, v45
	v_pk_add_f32 v[44:45], v[46:47], v[94:95] op_sel_hi:[1,0] neg_lo:[0,1] neg_hi:[0,1]
	v_add_u32_e32 v46, v106, v76
	v_exp_f32_e32 v112, v44
	v_exp_f32_e32 v113, v45
	v_pk_add_f32 v[44:45], v[48:49], v[94:95] op_sel_hi:[1,0] neg_lo:[0,1] neg_hi:[0,1]
	v_pk_add_f32 v[42:43], v[108:109], v[42:43]
	v_exp_f32_e32 v114, v44
	v_exp_f32_e32 v115, v45
	v_pk_add_f32 v[42:43], v[112:113], v[42:43]
	v_cvt_pk_bf16_f32 v36, v38, v39
	v_cvt_pk_bf16_f32 v37, v40, v41
	v_pk_add_f32 v[42:43], v[114:115], v[42:43]
	s_nop 0
	v_add_f32_e32 v116, v42, v43
	v_fmac_f32_e32 v116, v89, v96
	s_waitcnt lgkmcnt(0)
	v_mfma_f32_32x32x16_bf16 v[2:17], v[156:159], v[34:37], v[2:17]
	v_mov_b32_e32 v89, v116
	v_mov_b32_e32 v96, v94
	v_mfma_f32_32x32x16_bf16 v[18:33], v[164:167], v[34:37], v[18:33]
	v_cvt_pk_bf16_f32 v34, v110, v111
	v_cvt_pk_bf16_f32 v35, v108, v109
	v_cvt_pk_bf16_f32 v36, v112, v113
	v_cvt_pk_bf16_f32 v37, v114, v115
	s_nop 1
	v_mfma_f32_32x32x16_bf16 v[2:17], v[160:163], v[34:37], v[2:17]
	v_mfma_f32_32x32x16_bf16 v[18:33], v[168:171], v[34:37], v[18:33]
.LBB0_290:
	s_add_i32 s2, s8, 32
	s_cmp_gt_i32 s2, s9
	s_cbranch_scc1 .LBB0_298
	s_add_i32 s3, s8, 63
	s_cmp_le_i32 s3, s20
	s_cbranch_scc1 .LBB0_298
	v_add_u32_e32 v94, v107, v102
	ds_read_b128 v[34:37], v94
	ds_read_b128 v[108:111], v94 offset:32
	ds_read_b128 v[152:155], v94 offset:64
	ds_read_b128 v[112:115], v94 offset:96
	v_add_u32_e32 v172, v106, v76
	v_add_u32_e32 v173, 0x3000, v172
	v_add_u32_e32 v172, 0x2000, v172
	ds_read2_b64 v[156:159], v172 offset0:136 offset1:138
	ds_read2_b64 v[160:163], v172 offset0:140 offset1:142
	ds_read2_b64 v[164:167], v173 offset0:200 offset1:202
	ds_read2_b64 v[168:171], v173 offset0:204 offset1:206
	s_cmp_gt_i32 s3, s18
	s_cselect_b64 s[24:25], -1, 0
	s_cmp_le_i32 s2, s21
	s_waitcnt lgkmcnt(7)
	v_mfma_f32_32x32x16_bf16 v[34:49], v[34:37], v[58:61], 0
	s_cselect_b64 s[2:3], -1, 0
	s_or_b64 s[2:3], s[24:25], s[2:3]
	s_andn2_b64 vcc, exec, s[2:3]
	s_waitcnt lgkmcnt(6)
	v_mfma_f32_32x32x16_bf16 v[34:49], v[108:111], v[62:65], v[34:49]
	s_waitcnt lgkmcnt(5)
	v_mfma_f32_32x32x16_bf16 v[34:49], v[152:155], v[66:69], v[34:49]
	s_waitcnt lgkmcnt(4)
	v_mfma_f32_32x32x16_bf16 v[34:49], v[112:115], v[70:73], v[34:49]
	s_cbranch_vccnz .LBB0_294
	v_add_u32_e32 v94, s8, v82
	v_add_u32_e32 v107, 32, v94
	v_cmp_le_i32_e32 vcc, v107, v88
	v_cmp_gt_i32_e64 s[2:3], v107, v105
	s_and_b64 vcc, vcc, s[2:3]
	s_nop 5
	v_cndmask_b32_e32 v34, v180, v34, vcc
	v_cmp_lt_i32_e32 vcc, v107, v88
	v_cmp_ge_i32_e64 s[2:3], v107, v105
	s_and_b64 vcc, vcc, s[2:3]
	v_add_u32_e32 v107, 34, v94
	v_cndmask_b32_e32 v35, v180, v35, vcc
	v_cmp_le_i32_e32 vcc, v107, v88
	v_cmp_gt_i32_e64 s[2:3], v107, v105
	s_and_b64 vcc, vcc, s[2:3]
	v_add_u32_e32 v107, 35, v94
	v_cndmask_b32_e32 v36, v180, v36, vcc
	v_cmp_le_i32_e32 vcc, v107, v88
	v_cmp_gt_i32_e64 s[2:3], v107, v105
	s_and_b64 vcc, vcc, s[2:3]
	v_add_u32_e32 v107, 40, v94
	v_cndmask_b32_e32 v37, v180, v37, vcc
	v_cmp_le_i32_e32 vcc, v107, v88
	v_cmp_gt_i32_e64 s[2:3], v107, v105
	s_and_b64 vcc, vcc, s[2:3]
	v_add_u32_e32 v107, 41, v94
	v_cndmask_b32_e32 v38, v180, v38, vcc
	v_cmp_le_i32_e32 vcc, v107, v88
	v_cmp_gt_i32_e64 s[2:3], v107, v105
	s_and_b64 vcc, vcc, s[2:3]
	v_add_u32_e32 v107, 42, v94
	v_cndmask_b32_e32 v39, v180, v39, vcc
	v_cmp_le_i32_e32 vcc, v107, v88
	v_cmp_gt_i32_e64 s[2:3], v107, v105
	s_and_b64 vcc, vcc, s[2:3]
	v_add_u32_e32 v107, 43, v94
	v_cndmask_b32_e32 v40, v180, v40, vcc
	v_cmp_le_i32_e32 vcc, v107, v88
	v_cmp_gt_i32_e64 s[2:3], v107, v105
	s_and_b64 vcc, vcc, s[2:3]
	v_add_u32_e32 v107, 48, v94
	v_cndmask_b32_e32 v41, v180, v41, vcc
	v_cmp_le_i32_e32 vcc, v107, v88
	v_cmp_gt_i32_e64 s[2:3], v107, v105
	s_and_b64 vcc, vcc, s[2:3]
	v_add_u32_e32 v107, 49, v94
	v_cndmask_b32_e32 v42, v180, v42, vcc
	v_cmp_le_i32_e32 vcc, v107, v88
	v_cmp_gt_i32_e64 s[2:3], v107, v105
	s_and_b64 vcc, vcc, s[2:3]
	v_add_u32_e32 v107, 50, v94
	v_cndmask_b32_e32 v43, v180, v43, vcc
	v_cmp_le_i32_e32 vcc, v107, v88
	v_cmp_gt_i32_e64 s[2:3], v107, v105
	s_and_b64 vcc, vcc, s[2:3]
	v_add_u32_e32 v107, 51, v94
	v_cndmask_b32_e32 v44, v180, v44, vcc
	v_cmp_le_i32_e32 vcc, v107, v88
	v_cmp_gt_i32_e64 s[2:3], v107, v105
	s_and_b64 vcc, vcc, s[2:3]
	v_add_u32_e32 v107, 56, v94
	v_cndmask_b32_e32 v45, v180, v45, vcc
	v_cmp_le_i32_e32 vcc, v107, v88
	v_cmp_gt_i32_e64 s[2:3], v107, v105
	s_and_b64 vcc, vcc, s[2:3]
	v_add_u32_e32 v107, 57, v94
	v_cndmask_b32_e32 v46, v180, v46, vcc
	v_cmp_le_i32_e32 vcc, v107, v88
	v_cmp_gt_i32_e64 s[2:3], v107, v105
	s_and_b64 vcc, vcc, s[2:3]
	v_add_u32_e32 v107, 58, v94
	v_cndmask_b32_e32 v47, v180, v47, vcc
	v_cmp_le_i32_e32 vcc, v107, v88
	v_cmp_gt_i32_e64 s[2:3], v107, v105
	s_and_b64 vcc, vcc, s[2:3]
	v_add_u32_e32 v94, 59, v94
	v_cndmask_b32_e32 v48, v180, v48, vcc
	v_cmp_le_i32_e32 vcc, v94, v88
	v_cmp_gt_i32_e64 s[2:3], v94, v105
	s_and_b64 vcc, vcc, s[2:3]
	v_cndmask_b32_e32 v49, v180, v49, vcc

; #define LAS __attribute__((address_space(3)))
; __device__ __forceinline__ float ex2(float x) { return __builtin_amdgcn_exp2f(x); }
; template <int ND, int MODE>
; __device__ __forceinline__ void attn_sub(float& m, float& l, f32x16& o0, f32x16& o1, const bf16x8 (&qf)[ND], const LAS bf16_t* Ks, const LAS bf16_t* Vt,
;                                          int kr0, int kc0, int key0, int qpos, float c, bool need_mask, int r, int h) {
;     ...
;     float pv[16]; f32x2_t ps2 = {0.f, 0.f}; const f32x2_t c2 = {c, c}, mn2 = {mn, mn};
; #pragma unroll
;     for (int i = 0; i < 8; ++i) { f32x2_t tt = {s[2 * i], s[2 * i + 1]}; tt = (tt - mn2) * c2; pv[2 * i] = ex2(tt.x); pv[2 * i + 1] = ex2(tt.y); const f32x2_t pp = {pv[2 * i], pv[2 * i + 1]}; ps2 += pp; }
;     l = l * alpha + (ps2.x + ps2.y);
; #pragma unroll
;     for (int s2 = 0; s2 < 2; ++s2) {
;         const bf16x8 pb = pack8(pv[8 * s2 + 0], pv[8 * s2 + 1], pv[8 * s2 + 2], pv[8 * s2 + 3], pv[8 * s2 + 4], pv[8 * s2 + 5], pv[8 * s2 + 6], pv[8 * s2 + 7]);
;         const LAS bf16_t* vp = Vt + r * VP + kr0 + 16 * s2 + 4 * h;
;         const u32x2 a0l = *(const LAS u32x2*)vp, a0h = *(const LAS u32x2*)(vp + 8);
;         const u32x2 a1l = *(const LAS u32x2*)(vp + 32 * VP), a1h = *(const LAS u32x2*)(vp + 32 * VP + 8);
;         u32x4 a0 = {a0l.x, a0l.y, a0h.x, a0h.y}, a1 = {a1l.x, a1l.y, a1h.x, a1h.y};
;         o0 = __builtin_amdgcn_mfma_f32_32x32x16_bf16(__builtin_bit_cast(bf16x8, a0), pb, o0, 0, 0, 0);
;         o1 = __builtin_amdgcn_mfma_f32_32x32x16_bf16(__builtin_bit_cast(bf16x8, a1), pb, o1, 0, 0, 0);
;     }
.LBB0_297:
	v_pk_add_f32 v[34:35], v[34:35], v[94:95] op_sel_hi:[1,0] neg_lo:[0,1] neg_hi:[0,1]
	v_pk_add_f32 v[36:37], v[36:37], v[94:95] op_sel_hi:[1,0] neg_lo:[0,1] neg_hi:[0,1]
	v_exp_f32_e32 v34, v34
	v_exp_f32_e32 v35, v35
	v_exp_f32_e32 v36, v36
	v_exp_f32_e32 v37, v37
	v_pk_add_f32 v[38:39], v[38:39], v[94:95] op_sel_hi:[1,0] neg_lo:[0,1] neg_hi:[0,1]
	v_pk_add_f32 v[40:41], v[40:41], v[94:95] op_sel_hi:[1,0] neg_lo:[0,1] neg_hi:[0,1]
	v_exp_f32_e32 v38, v38
	v_exp_f32_e32 v39, v39
	v_exp_f32_e32 v40, v40
	v_exp_f32_e32 v41, v41
	v_pk_add_f32 v[42:43], v[42:43], v[94:95] op_sel_hi:[1,0] neg_lo:[0,1] neg_hi:[0,1]
	v_pk_add_f32 v[108:109], v[34:35], 0 op_sel_hi:[1,0]
	v_exp_f32_e32 v110, v42
	v_exp_f32_e32 v111, v43
	v_pk_add_f32 v[108:109], v[36:37], v[108:109]
	v_pk_add_f32 v[44:45], v[44:45], v[94:95] op_sel_hi:[1,0] neg_lo:[0,1] neg_hi:[0,1]
	v_pk_add_f32 v[108:109], v[38:39], v[108:109]
	v_cvt_pk_bf16_f32 v34, v34, v35
	v_pk_add_f32 v[108:109], v[40:41], v[108:109]
	v_cvt_pk_bf16_f32 v35, v36, v37
	v_pk_add_f32 v[42:43], v[110:111], v[108:109]
	v_exp_f32_e32 v108, v44
	v_exp_f32_e32 v109, v45
	v_pk_add_f32 v[44:45], v[46:47], v[94:95] op_sel_hi:[1,0] neg_lo:[0,1] neg_hi:[0,1]
	v_add_u32_e32 v46, v106, v76
	v_exp_f32_e32 v112, v44
	v_exp_f32_e32 v113, v45
	v_pk_add_f32 v[44:45], v[48:49], v[94:95] op_sel_hi:[1,0] neg_lo:[0,1] neg_hi:[0,1]
	v_pk_add_f32 v[42:43], v[108:109], v[42:43]
	v_exp_f32_e32 v114, v44
	v_exp_f32_e32 v115, v45
	v_pk_add_f32 v[42:43], v[112:113], v[42:43]
	v_cvt_pk_bf16_f32 v36, v38, v39
	v_cvt_pk_bf16_f32 v37, v40, v41
	v_pk_add_f32 v[42:43], v[114:115], v[42:43]
	s_nop 0
	v_add_f32_e32 v107, v42, v43
	v_fmac_f32_e32 v107, v89, v96
	s_waitcnt lgkmcnt(0)
	v_mfma_f32_32x32x16_bf16 v[2:17], v[156:159], v[34:37], v[2:17]
	v_mov_b32_e32 v89, v107
	v_mov_b32_e32 v96, v94
	v_mfma_f32_32x32x16_bf16 v[18:33], v[164:167], v[34:37], v[18:33]
	v_cvt_pk_bf16_f32 v34, v110, v111
	v_cvt_pk_bf16_f32 v35, v108, v109
	v_cvt_pk_bf16_f32 v36, v112, v113
	v_cvt_pk_bf16_f32 v37, v114, v115
	s_nop 1
	v_mfma_f32_32x32x16_bf16 v[2:17], v[160:163], v[34:37], v[2:17]
	v_mfma_f32_32x32x16_bf16 v[18:33], v[168:171], v[34:37], v[18:33]

; #define LAS __attribute__((address_space(3)))
; __device__ __forceinline__ int rowi32(int i, int h) { return (i & 3) + 8 * (i >> 2) + 4 * h; }
; template <int ND>
; __device__ __forceinline__ f32x16 qk_sub(const bf16x8 (&qf)[ND], const LAS bf16_t* Ks, int kr0, int kc0, int r, int h) {
;     f32x16 s;
; #pragma unroll
;     for (int i = 0; i < 16; ++i) s[i] = 0.f;
; #pragma unroll
;     for (int ks = 0; ks < ND; ++ks) { const bf16x8 a = *(const LAS bf16x8*)(Ks + (kr0 + r) * KP + kc0 + 16 * ks + 8 * h); s = __builtin_amdgcn_mfma_f32_32x32x16_bf16(a, qf[ks], s, 0, 0, 0); }
;     return s;
; }
; template <int MODE> __device__ __forceinline__ bool key_ok(int key, int qpos) {
;     if (MODE == 0) return key <= qpos;
;     if (MODE == 1) return (key <= qpos) && (key > qpos - 512);
;     return 16 * key + 31 <= qpos;
; }
; template <int ND, int MODE>
; __device__ __forceinline__ void attn_sub(float& m, float& l, f32x16& o0, f32x16& o1, const bf16x8 (&qf)[ND], const LAS bf16_t* Ks, const LAS bf16_t* Vt,
;                                          int kr0, int kc0, int key0, int qpos, float c, bool need_mask, int r, int h) {
;     f32x16 s = qk_sub<ND>(qf, Ks, kr0, kc0, r, h);
;     if (need_mask) {
; #pragma unroll
;         for (int i = 0; i < 16; ++i) { const int key = key0 + rowi32(i, h); s[i] = key_ok<MODE>(key, qpos) ? s[i] : NEG; }
;     }
; __device__ __forceinline__ void phase_cmp(const Params& p, LAS unsigned char* lds, const bf16_t* Z, const float* G, const bf16_t* KC, const bf16_t* ACCW, float* ACC, int* IDX, ...
;     ...
;         for (int t = 0, bi = 0; t < nt; ++t, bi ^= 1) {
;             const LAS bf16_t* Ks = Ks0 + bi * TLB; const LAS bf16_t* Vt = Ks + 64 * KP;
; #pragma unroll
;             for (int sub = 0; sub < 2; ++sub) {
;                 const int k0 = 64 * t + 32 * sub;
;                 if (16 * k0 + 31 > q0w + 31) continue;
;                 const bool nm = (16 * (k0 + 31) + 31 > q0w);
;                 attn_sub<4, 2>(m, l, o0, o1, qf, Ks, Vt, 32 * sub, 0, k0, qpos, 1.0f, nm, r, h);
.LBB0_362:
	s_mul_i32 s26, s22, 0x4800
	s_add_i32 s26, s26, 0
	v_add_u32_e32 v115, s26, v120
	s_cmp_gt_i32 s21, s41
	v_add_u32_e32 v99, s26, v122
	s_cbranch_scc1 .LBB0_367
	v_add_u32_e32 v116, v115, v122
	ds_read_b128 v[34:37], v116
	ds_read_b128 v[142:145], v116 offset:32
	ds_read_b128 v[152:155], v116 offset:64
	ds_read_b128 v[174:177], v116 offset:96
	v_add_u32_e32 v172, v99, v76
	v_add_u32_e32 v173, 0x3000, v172
	v_add_u32_e32 v172, 0x2000, v172
	ds_read2_b64 v[156:159], v172 offset0:128 offset1:130
	ds_read2_b64 v[160:163], v172 offset0:132 offset1:134
	ds_read2_b64 v[164:167], v173 offset0:192 offset1:194
	ds_read2_b64 v[168:171], v173 offset0:196 offset1:198
	s_add_i32 s26, s21, 0x20f
	s_cmp_le_i32 s26, s41
	s_waitcnt lgkmcnt(7)
	v_mfma_f32_32x32x16_bf16 v[34:49], v[34:37], v[50:53], 0
	s_waitcnt lgkmcnt(6)
	v_mfma_f32_32x32x16_bf16 v[34:49], v[142:145], v[54:57], v[34:49]
	s_waitcnt lgkmcnt(5)
	v_mfma_f32_32x32x16_bf16 v[34:49], v[152:155], v[58:61], v[34:49]
	s_waitcnt lgkmcnt(4)
	v_mfma_f32_32x32x16_bf16 v[34:49], v[174:177], v[62:65], v[34:49]
	s_cbranch_scc1 .LBB0_365
	v_add_u32_e32 v116, s21, v121
	v_add_u32_e32 v142, 31, v116
	v_cmp_le_i32_e32 vcc, v142, v96
	v_add_u32_e32 v142, 47, v116
	s_nop 6
	v_cndmask_b32_e32 v34, v180, v34, vcc
	v_cmp_le_i32_e32 vcc, v142, v96
	v_add_u32_e32 v142, 63, v116
	s_nop 0
	v_cndmask_b32_e32 v35, v180, v35, vcc
	v_cmp_le_i32_e32 vcc, v142, v96
	v_add_u32_e32 v142, 0x9f, v116
	s_nop 0
	v_cndmask_b32_e32 v36, v180, v36, vcc
	v_cmp_le_i32_e32 vcc, v116, v95
	s_nop 1
	v_cndmask_b32_e32 v37, v180, v37, vcc
	v_cmp_le_i32_e32 vcc, v142, v96
	v_add_u32_e32 v142, 0xaf, v116
	s_nop 0
	v_cndmask_b32_e32 v38, v180, v38, vcc
	v_cmp_le_i32_e32 vcc, v142, v96
	v_add_u32_e32 v142, 0xbf, v116
	s_nop 0
	v_cndmask_b32_e32 v39, v180, v39, vcc
	v_cmp_le_i32_e32 vcc, v142, v96
	v_add_u32_e32 v142, 0x11f, v116
	s_nop 0
	v_cndmask_b32_e32 v40, v180, v40, vcc
	v_cmp_le_i32_e32 vcc, v116, v97
	s_nop 1
	v_cndmask_b32_e32 v41, v180, v41, vcc
	v_cmp_le_i32_e32 vcc, v142, v96
	v_add_u32_e32 v142, 0x12f, v116
	s_nop 0
	v_cndmask_b32_e32 v42, v180, v42, vcc
	v_cmp_le_i32_e32 vcc, v142, v96
	v_add_u32_e32 v142, 0x13f, v116
	s_nop 0
	v_cndmask_b32_e32 v43, v180, v43, vcc
	v_cmp_le_i32_e32 vcc, v142, v96
	v_add_u32_e32 v142, 0x19f, v116
	s_nop 0
	v_cndmask_b32_e32 v44, v180, v44, vcc
	v_cmp_le_i32_e32 vcc, v116, v139
	s_nop 1
	v_cndmask_b32_e32 v45, v180, v45, vcc
	v_cmp_le_i32_e32 vcc, v142, v96
	v_add_u32_e32 v142, 0x1af, v116
	s_nop 0
	v_cndmask_b32_e32 v46, v180, v46, vcc
	v_cmp_le_i32_e32 vcc, v142, v96
	v_add_u32_e32 v142, 0x1bf, v116
	s_nop 0
	v_cndmask_b32_e32 v47, v180, v47, vcc
	v_cmp_le_i32_e32 vcc, v142, v96
	s_nop 1
	v_cndmask_b32_e32 v48, v180, v48, vcc
	v_cmp_le_i32_e32 vcc, v116, v140
	s_nop 1
	v_cndmask_b32_e32 v49, v180, v49, vcc

; #define LAS __attribute__((address_space(3)))
; __device__ __forceinline__ float ex2(float x) { return __builtin_amdgcn_exp2f(x); }
; template <int ND, int MODE>
; __device__ __forceinline__ void attn_sub(float& m, float& l, f32x16& o0, f32x16& o1, const bf16x8 (&qf)[ND], const LAS bf16_t* Ks, const LAS bf16_t* Vt,
;                                          int kr0, int kc0, int key0, int qpos, float c, bool need_mask, int r, int h) {
;     ...
;     float pv[16]; f32x2_t ps2 = {0.f, 0.f}; const f32x2_t c2 = {c, c}, mn2 = {mn, mn};
; #pragma unroll
;     for (int i = 0; i < 8; ++i) { f32x2_t tt = {s[2 * i], s[2 * i + 1]}; tt = (tt - mn2) * c2; pv[2 * i] = ex2(tt.x); pv[2 * i + 1] = ex2(tt.y); const f32x2_t pp = {pv[2 * i], pv[2 * i + 1]}; ps2 += pp; }
;     l = l * alpha + (ps2.x + ps2.y);
; #pragma unroll
;     for (int s2 = 0; s2 < 2; ++s2) {
;         const bf16x8 pb = pack8(pv[8 * s2 + 0], pv[8 * s2 + 1], pv[8 * s2 + 2], pv[8 * s2 + 3], pv[8 * s2 + 4], pv[8 * s2 + 5], pv[8 * s2 + 6], pv[8 * s2 + 7]);
;         const LAS bf16_t* vp = Vt + r * VP + kr0 + 16 * s2 + 4 * h;
;         const u32x2 a0l = *(const LAS u32x2*)vp, a0h = *(const LAS u32x2*)(vp + 8);
;         const u32x2 a1l = *(const LAS u32x2*)(vp + 32 * VP), a1h = *(const LAS u32x2*)(vp + 32 * VP + 8);
;         u32x4 a0 = {a0l.x, a0l.y, a0h.x, a0h.y}, a1 = {a1l.x, a1l.y, a1h.x, a1h.y};
;         o0 = __builtin_amdgcn_mfma_f32_32x32x16_bf16(__builtin_bit_cast(bf16x8, a0), pb, o0, 0, 0, 0);
;         o1 = __builtin_amdgcn_mfma_f32_32x32x16_bf16(__builtin_bit_cast(bf16x8, a1), pb, o1, 0, 0, 0);
;     }
; __device__ __forceinline__ void phase_cmp(const Params& p, LAS unsigned char* lds, const bf16_t* Z, const float* G, const bf16_t* KC, const bf16_t* ACCW, float* ACC, int* IDX, ...
;     ...
; #pragma unroll
;             for (int sub = 0; sub < 2; ++sub) {
;                 const int k0 = 64 * t + 32 * sub;
;                 if (16 * k0 + 31 > q0w + 31) continue;
;                 const bool nm = (16 * (k0 + 31) + 31 > q0w);
;                 attn_sub<4, 2>(m, l, o0, o1, qf, Ks, Vt, 32 * sub, 0, k0, qpos, 1.0f, nm, r, h);
.LBB0_370:
	v_pk_add_f32 v[34:35], v[34:35], v[116:117] op_sel_hi:[1,0] neg_lo:[0,1] neg_hi:[0,1]
	v_pk_add_f32 v[36:37], v[36:37], v[116:117] op_sel_hi:[1,0] neg_lo:[0,1] neg_hi:[0,1]
	v_exp_f32_e32 v34, v34
	v_exp_f32_e32 v35, v35
	v_exp_f32_e32 v36, v36
	v_exp_f32_e32 v37, v37
	v_pk_add_f32 v[38:39], v[38:39], v[116:117] op_sel_hi:[1,0] neg_lo:[0,1] neg_hi:[0,1]
	v_pk_add_f32 v[40:41], v[40:41], v[116:117] op_sel_hi:[1,0] neg_lo:[0,1] neg_hi:[0,1]
	v_exp_f32_e32 v38, v38
	v_exp_f32_e32 v39, v39
	v_exp_f32_e32 v40, v40
	v_exp_f32_e32 v41, v41
	v_pk_add_f32 v[42:43], v[42:43], v[116:117] op_sel_hi:[1,0] neg_lo:[0,1] neg_hi:[0,1]
	v_pk_add_f32 v[142:143], v[34:35], 0 op_sel_hi:[1,0]
	v_exp_f32_e32 v144, v42
	v_exp_f32_e32 v145, v43
	v_pk_add_f32 v[142:143], v[36:37], v[142:143]
	v_pk_add_f32 v[44:45], v[44:45], v[116:117] op_sel_hi:[1,0] neg_lo:[0,1] neg_hi:[0,1]
	v_pk_add_f32 v[142:143], v[38:39], v[142:143]
	v_cvt_pk_bf16_f32 v34, v34, v35
	v_pk_add_f32 v[142:143], v[40:41], v[142:143]
	v_cvt_pk_bf16_f32 v35, v36, v37
	v_pk_add_f32 v[42:43], v[144:145], v[142:143]
	v_exp_f32_e32 v142, v44
	v_exp_f32_e32 v143, v45
	v_pk_add_f32 v[44:45], v[46:47], v[116:117] op_sel_hi:[1,0] neg_lo:[0,1] neg_hi:[0,1]
	v_add_u32_e32 v46, v99, v76
	v_exp_f32_e32 v146, v44
	v_exp_f32_e32 v147, v45
	v_pk_add_f32 v[44:45], v[48:49], v[116:117] op_sel_hi:[1,0] neg_lo:[0,1] neg_hi:[0,1]
	v_pk_add_f32 v[42:43], v[142:143], v[42:43]
	v_exp_f32_e32 v148, v44
	v_exp_f32_e32 v149, v45
	v_pk_add_f32 v[42:43], v[146:147], v[42:43]
	v_cvt_pk_bf16_f32 v36, v38, v39
	v_cvt_pk_bf16_f32 v37, v40, v41
	v_pk_add_f32 v[42:43], v[148:149], v[42:43]
	s_nop 0
	v_add_f32_e32 v150, v42, v43
	v_fmac_f32_e32 v150, v141, v104
	s_waitcnt lgkmcnt(0)
	v_mfma_f32_32x32x16_bf16 v[2:17], v[156:159], v[34:37], v[2:17]
	v_mov_b32_e32 v141, v150
	v_mfma_f32_32x32x16_bf16 v[18:33], v[164:167], v[34:37], v[18:33]
	v_cvt_pk_bf16_f32 v34, v144, v145
	v_cvt_pk_bf16_f32 v35, v142, v143
	v_cvt_pk_bf16_f32 v36, v146, v147
	v_cvt_pk_bf16_f32 v37, v148, v149
	s_nop 1
	v_mfma_f32_32x32x16_bf16 v[2:17], v[160:163], v[34:37], v[2:17]
	v_mfma_f32_32x32x16_bf16 v[18:33], v[168:171], v[34:37], v[18:33]
	s_add_i32 s26, s21, 0x200
	s_cmp_gt_i32 s26, s41
	s_cbranch_scc1 .LBB0_368
.LBB0_371:
	v_add_u32_e32 v104, v115, v125
	ds_read_b128 v[34:37], v104
	ds_read_b128 v[142:145], v104 offset:32
	ds_read_b128 v[152:155], v104 offset:64
	ds_read_b128 v[174:177], v104 offset:96
	v_add_u32_e32 v172, v99, v76
	v_add_u32_e32 v173, 0x3000, v172
	v_add_u32_e32 v172, 0x2000, v172
	ds_read2_b64 v[156:159], v172 offset0:136 offset1:138
	ds_read2_b64 v[160:163], v172 offset0:140 offset1:142
	ds_read2_b64 v[164:167], v173 offset0:200 offset1:202
	ds_read2_b64 v[168:171], v173 offset0:204 offset1:206
	s_cmp_le_i32 s21, s20
	s_waitcnt lgkmcnt(7)
	v_mfma_f32_32x32x16_bf16 v[34:49], v[34:37], v[50:53], 0
	s_waitcnt lgkmcnt(6)
	v_mfma_f32_32x32x16_bf16 v[34:49], v[142:145], v[54:57], v[34:49]
	s_waitcnt lgkmcnt(5)
	v_mfma_f32_32x32x16_bf16 v[34:49], v[152:155], v[58:61], v[34:49]
	s_waitcnt lgkmcnt(4)
	v_mfma_f32_32x32x16_bf16 v[34:49], v[174:177], v[62:65], v[34:49]
	s_cbranch_scc1 .LBB0_373
	v_add_u32_e32 v104, s21, v121
	v_add_u32_e32 v142, 0x21f, v104
	v_cmp_le_i32_e32 vcc, v142, v96
	v_add_u32_e32 v142, 0x22f, v104
	v_add_u32_e32 v115, 0x200, v104
	s_nop 5
	v_cndmask_b32_e32 v34, v180, v34, vcc
	v_cmp_le_i32_e32 vcc, v142, v96
	v_add_u32_e32 v142, 0x23f, v104
	s_nop 0
	v_cndmask_b32_e32 v35, v180, v35, vcc
	v_cmp_le_i32_e32 vcc, v142, v96
	v_add_u32_e32 v142, 0x29f, v104
	s_nop 0
	v_cndmask_b32_e32 v36, v180, v36, vcc
	v_cmp_le_i32_e32 vcc, v115, v95
	s_nop 1
	v_cndmask_b32_e32 v37, v180, v37, vcc
	v_cmp_le_i32_e32 vcc, v142, v96
	v_add_u32_e32 v142, 0x2af, v104
	s_nop 0
	v_cndmask_b32_e32 v38, v180, v38, vcc
	v_cmp_le_i32_e32 vcc, v142, v96
	v_add_u32_e32 v142, 0x2bf, v104
	s_nop 0
	v_cndmask_b32_e32 v39, v180, v39, vcc
	v_cmp_le_i32_e32 vcc, v142, v96
	v_add_u32_e32 v142, 0x31f, v104
	s_nop 0
	v_cndmask_b32_e32 v40, v180, v40, vcc
	v_cmp_le_i32_e32 vcc, v115, v97
	s_nop 1
	v_cndmask_b32_e32 v41, v180, v41, vcc
	v_cmp_le_i32_e32 vcc, v142, v96
	v_add_u32_e32 v142, 0x32f, v104
	s_nop 0
	v_cndmask_b32_e32 v42, v180, v42, vcc
	v_cmp_le_i32_e32 vcc, v142, v96
	v_add_u32_e32 v142, 0x33f, v104
	s_nop 0
	v_cndmask_b32_e32 v43, v180, v43, vcc
	v_cmp_le_i32_e32 vcc, v142, v96
	s_nop 1
	v_cndmask_b32_e32 v44, v180, v44, vcc
	v_cmp_le_i32_e32 vcc, v115, v139
	v_add_u32_e32 v115, 0x39f, v104
	s_nop 0
	v_cndmask_b32_e32 v45, v180, v45, vcc
	v_cmp_le_i32_e32 vcc, v115, v96
	v_add_u32_e32 v115, 0x3af, v104
	s_nop 0
	v_cndmask_b32_e32 v46, v180, v46, vcc
	v_cmp_le_i32_e32 vcc, v115, v96
	v_add_u32_e32 v115, 0x3bf, v104
	v_add_u32_e32 v104, 0x3cf, v104
	v_cndmask_b32_e32 v47, v180, v47, vcc
	v_cmp_le_i32_e32 vcc, v115, v96
	s_nop 1
	v_cndmask_b32_e32 v48, v180, v48, vcc
	v_cmp_le_i32_e32 vcc, v104, v96
	s_nop 1
	v_cndmask_b32_e32 v49, v180, v49, vcc

; #define LAS __attribute__((address_space(3)))
; __device__ __forceinline__ float ex2(float x) { return __builtin_amdgcn_exp2f(x); }
; #define TL_NEXT(Kg, kpitch, Vg, vpitch, t, t1, bi) do { if ((t) + 1 < (t1)) { TL_WRITE((bi) ^ 1); if ((t) + 2 < (t1)) TL_FETCH(Kg, kpitch, Vg, vpitch, (t) + 2); } __syncthreads(); } while (0)
; template <int ND, int MODE>
; __device__ __forceinline__ void attn_sub(float& m, float& l, f32x16& o0, f32x16& o1, const bf16x8 (&qf)[ND], const LAS bf16_t* Ks, const LAS bf16_t* Vt,
;                                          int kr0, int kc0, int key0, int qpos, float c, bool need_mask, int r, int h) {
;     ...
;     float pv[16]; f32x2_t ps2 = {0.f, 0.f}; const f32x2_t c2 = {c, c}, mn2 = {mn, mn};
; #pragma unroll
;     for (int i = 0; i < 8; ++i) { f32x2_t tt = {s[2 * i], s[2 * i + 1]}; tt = (tt - mn2) * c2; pv[2 * i] = ex2(tt.x); pv[2 * i + 1] = ex2(tt.y); const f32x2_t pp = {pv[2 * i], pv[2 * i + 1]}; ps2 += pp; }
;     l = l * alpha + (ps2.x + ps2.y);
; #pragma unroll
;     for (int s2 = 0; s2 < 2; ++s2) {
;         const bf16x8 pb = pack8(pv[8 * s2 + 0], pv[8 * s2 + 1], pv[8 * s2 + 2], pv[8 * s2 + 3], pv[8 * s2 + 4], pv[8 * s2 + 5], pv[8 * s2 + 6], pv[8 * s2 + 7]);
;         const LAS bf16_t* vp = Vt + r * VP + kr0 + 16 * s2 + 4 * h;
;         const u32x2 a0l = *(const LAS u32x2*)vp, a0h = *(const LAS u32x2*)(vp + 8);
;         const u32x2 a1l = *(const LAS u32x2*)(vp + 32 * VP), a1h = *(const LAS u32x2*)(vp + 32 * VP + 8);
;         u32x4 a0 = {a0l.x, a0l.y, a0h.x, a0h.y}, a1 = {a1l.x, a1l.y, a1h.x, a1h.y};
;         o0 = __builtin_amdgcn_mfma_f32_32x32x16_bf16(__builtin_bit_cast(bf16x8, a0), pb, o0, 0, 0, 0);
;         o1 = __builtin_amdgcn_mfma_f32_32x32x16_bf16(__builtin_bit_cast(bf16x8, a1), pb, o1, 0, 0, 0);
;     }
; __device__ __forceinline__ void phase_cmp(const Params& p, LAS unsigned char* lds, const bf16_t* Z, const float* G, const bf16_t* KC, const bf16_t* ACCW, float* ACC, int* IDX, ...
;     ...
;             TL_NEXT(Kg, 64, Vg, 64, t, nt, bi);
;         }
.LBB0_376:
	v_pk_add_f32 v[34:35], v[34:35], v[104:105] op_sel_hi:[1,0] neg_lo:[0,1] neg_hi:[0,1]
	v_pk_add_f32 v[36:37], v[36:37], v[104:105] op_sel_hi:[1,0] neg_lo:[0,1] neg_hi:[0,1]
	v_exp_f32_e32 v34, v34
	v_exp_f32_e32 v35, v35
	v_exp_f32_e32 v36, v36
	v_exp_f32_e32 v37, v37
	v_pk_add_f32 v[38:39], v[38:39], v[104:105] op_sel_hi:[1,0] neg_lo:[0,1] neg_hi:[0,1]
	v_pk_add_f32 v[40:41], v[40:41], v[104:105] op_sel_hi:[1,0] neg_lo:[0,1] neg_hi:[0,1]
	v_exp_f32_e32 v38, v38
	v_exp_f32_e32 v39, v39
	v_exp_f32_e32 v40, v40
	v_exp_f32_e32 v41, v41
	v_pk_add_f32 v[42:43], v[42:43], v[104:105] op_sel_hi:[1,0] neg_lo:[0,1] neg_hi:[0,1]
	v_pk_add_f32 v[142:143], v[34:35], 0 op_sel_hi:[1,0]
	v_exp_f32_e32 v144, v42
	v_exp_f32_e32 v145, v43
	v_pk_add_f32 v[142:143], v[36:37], v[142:143]
	v_pk_add_f32 v[44:45], v[44:45], v[104:105] op_sel_hi:[1,0] neg_lo:[0,1] neg_hi:[0,1]
	v_pk_add_f32 v[142:143], v[38:39], v[142:143]
	v_cvt_pk_bf16_f32 v34, v34, v35
	v_pk_add_f32 v[142:143], v[40:41], v[142:143]
	v_cvt_pk_bf16_f32 v35, v36, v37
	v_pk_add_f32 v[42:43], v[144:145], v[142:143]
	v_exp_f32_e32 v142, v44
	v_exp_f32_e32 v143, v45
	v_pk_add_f32 v[44:45], v[46:47], v[104:105] op_sel_hi:[1,0] neg_lo:[0,1] neg_hi:[0,1]
	v_add_u32_e32 v46, v99, v76
	v_exp_f32_e32 v146, v44
	v_exp_f32_e32 v147, v45
	v_pk_add_f32 v[44:45], v[48:49], v[104:105] op_sel_hi:[1,0] neg_lo:[0,1] neg_hi:[0,1]
	v_pk_add_f32 v[42:43], v[142:143], v[42:43]
	v_exp_f32_e32 v148, v44
	v_exp_f32_e32 v149, v45
	v_pk_add_f32 v[42:43], v[146:147], v[42:43]
	v_cvt_pk_bf16_f32 v36, v38, v39
	v_pk_add_f32 v[42:43], v[148:149], v[42:43]
	v_cvt_pk_bf16_f32 v37, v40, v41
	s_nop 0
	v_add_f32_e32 v115, v42, v43
	s_waitcnt lgkmcnt(0)
	v_mfma_f32_32x32x16_bf16 v[2:17], v[156:159], v[34:37], v[2:17]
	v_fmac_f32_e32 v115, v141, v116
	v_mov_b32_e32 v141, v115
	v_mfma_f32_32x32x16_bf16 v[18:33], v[164:167], v[34:37], v[18:33]
	v_cvt_pk_bf16_f32 v34, v144, v145
	v_cvt_pk_bf16_f32 v35, v142, v143
	v_cvt_pk_bf16_f32 v36, v146, v147
	v_cvt_pk_bf16_f32 v37, v148, v149
	s_nop 1
	v_mfma_f32_32x32x16_bf16 v[2:17], v[160:163], v[34:37], v[2:17]
	v_mfma_f32_32x32x16_bf16 v[18:33], v[168:171], v[34:37], v[18:33]
	s_add_i32 s26, s23, 1
	s_xor_b32 s22, s22, 1
	s_cmp_ge_u32 s26, s17
	s_cbranch_scc1 .LBB0_379

; __device__ __forceinline__ float ex2(float x) { return __builtin_amdgcn_exp2f(x); }
; __device__ __forceinline__ void phase_cmp(const Params& p, LAS unsigned char* lds, const bf16_t* Z, const float* G, const bf16_t* KC, const bf16_t* ACCW, float* ACC, int* IDX, ...
;     ...
; #pragma unroll
;                     for (int g4 = 0; g4 < 4; ++g4) {
;                         float sum4 = 0.f, p3 = 0.f;
; #pragma unroll
;                         for (int e = 0; e < 4; ++e) { const int key = k0 + 8 * g4 + 4 * h + e; const float pv = (16 * key + 31 <= qpos) ? ex2(s[4 * g4 + e] - m) * invL : 0.f; sum4 += pv; if (e == 3) p3 = pv; }
;                         const int j = (k0 >> 2) + 2 * g4 + h;
;                         __hip_atomic_fetch_add((unsigned*)(PS + j * 64 + ql), (unsigned)(sum4 * 268435456.f + 0.5f), __ATOMIC_RELAXED, __HIP_MEMORY_SCOPE_WORKGROUP);
;                         if (j + 1 < 256) __hip_atomic_fetch_add((unsigned*)(PS + (j + 1) * 64 + ql), (unsigned)(p3 * 268435456.f + 0.5f), __ATOMIC_RELAXED, __HIP_MEMORY_SCOPE_WORKGROUP);
;                     }
.Lc2_fast0:
	s_nop 11
	v_sub_f32_e32 v2, v2, v104
	v_sub_f32_e32 v3, v3, v104
	v_sub_f32_e32 v4, v4, v104
	v_sub_f32_e32 v5, v5, v104
	v_exp_f32_e32 v2, v2
	v_exp_f32_e32 v3, v3
	v_exp_f32_e32 v4, v4
	v_exp_f32_e32 v5, v5
	v_mul_f32_e32 v2, v34, v2
	v_mul_f32_e32 v3, v34, v3
	v_mul_f32_e32 v4, v34, v4
	v_mul_f32_e32 v5, v34, v5
	v_add_f32_e32 v2, v3, v2
	v_add_f32_e32 v2, v4, v2
	v_add_f32_e32 v2, v5, v2
	v_fma_f32 v2, v2, s55, 0.5
	v_cvt_u32_f32_e32 v2, v2
	v_lshlrev_b32_e32 v28, 8, v27
	v_add_u32_e32 v28, v135, v28
	ds_add_u32 v28, v2 offset:40960
	v_fma_f32 v5, v5, s55, 0.5
	v_cvt_u32_f32_e32 v5, v5
	v_cmp_gt_u32_e32 vcc, s57, v27
	s_and_saveexec_b64 s[18:19], vcc
	ds_add_u32 v28, v5 offset:41216
	s_or_b64 exec, exec, s[18:19]
	v_sub_f32_e32 v6, v6, v104
	v_sub_f32_e32 v7, v7, v104
	v_sub_f32_e32 v8, v8, v104
	v_sub_f32_e32 v9, v9, v104
	v_exp_f32_e32 v6, v6
	v_exp_f32_e32 v7, v7
	v_exp_f32_e32 v8, v8
	v_exp_f32_e32 v9, v9
	v_mul_f32_e32 v6, v34, v6
	v_mul_f32_e32 v7, v34, v7
	v_mul_f32_e32 v8, v34, v8
	v_mul_f32_e32 v9, v34, v9
	v_add_f32_e32 v6, v7, v6
	v_add_f32_e32 v6, v8, v6
	v_add_f32_e32 v6, v9, v6
	v_fma_f32 v6, v6, s55, 0.5
	v_cvt_u32_f32_e32 v6, v6
	v_or_b32_e32 v29, 2, v27
	v_lshlrev_b32_e32 v28, 8, v29
	v_add_u32_e32 v28, v135, v28
	ds_add_u32 v28, v6 offset:40960
	v_fma_f32 v9, v9, s55, 0.5
	v_cvt_u32_f32_e32 v9, v9
	v_cmp_gt_u32_e32 vcc, s57, v29
	s_and_saveexec_b64 s[18:19], vcc
	ds_add_u32 v28, v9 offset:41216
	s_or_b64 exec, exec, s[18:19]
	v_sub_f32_e32 v10, v10, v104
	v_sub_f32_e32 v11, v11, v104
	v_sub_f32_e32 v12, v12, v104
	v_sub_f32_e32 v13, v13, v104
	v_exp_f32_e32 v10, v10
	v_exp_f32_e32 v11, v11
	v_exp_f32_e32 v12, v12
	v_exp_f32_e32 v13, v13
	v_mul_f32_e32 v10, v34, v10
	v_mul_f32_e32 v11, v34, v11
	v_mul_f32_e32 v12, v34, v12
	v_mul_f32_e32 v13, v34, v13
	v_add_f32_e32 v10, v11, v10
	v_add_f32_e32 v10, v12, v10
	v_add_f32_e32 v10, v13, v10
	v_fma_f32 v10, v10, s55, 0.5
	v_cvt_u32_f32_e32 v10, v10
	v_or_b32_e32 v29, 4, v27
	v_lshlrev_b32_e32 v28, 8, v29
	v_add_u32_e32 v28, v135, v28
	ds_add_u32 v28, v10 offset:40960
	v_fma_f32 v13, v13, s55, 0.5
	v_cvt_u32_f32_e32 v13, v13
	v_cmp_gt_u32_e32 vcc, s57, v29
	s_and_saveexec_b64 s[18:19], vcc
	ds_add_u32 v28, v13 offset:41216
	s_or_b64 exec, exec, s[18:19]
	v_sub_f32_e32 v14, v14, v104
	v_sub_f32_e32 v15, v15, v104
	v_sub_f32_e32 v16, v16, v104
	v_sub_f32_e32 v17, v17, v104
	v_exp_f32_e32 v14, v14
	v_exp_f32_e32 v15, v15
	v_exp_f32_e32 v16, v16
	v_exp_f32_e32 v17, v17
	v_mul_f32_e32 v14, v34, v14
	v_mul_f32_e32 v15, v34, v15
	v_mul_f32_e32 v16, v34, v16
	v_mul_f32_e32 v17, v34, v17
	v_add_f32_e32 v14, v15, v14
	v_add_f32_e32 v14, v16, v14
	v_add_f32_e32 v14, v17, v14
	v_fma_f32 v14, v14, s55, 0.5
	v_cvt_u32_f32_e32 v14, v14
	v_or_b32_e32 v29, 6, v27
	v_lshlrev_b32_e32 v28, 8, v29
	v_add_u32_e32 v28, v135, v28
	ds_add_u32 v28, v14 offset:40960
	v_fma_f32 v17, v17, s55, 0.5
	v_cvt_u32_f32_e32 v17, v17
	v_cmp_gt_u32_e32 vcc, s57, v29
	s_and_saveexec_b64 s[18:19], vcc
	ds_add_u32 v28, v17 offset:41216
	s_or_b64 exec, exec, s[18:19]
	s_branch .LBB0_410
; #define LAS __attribute__((address_space(3)))
; __device__ __forceinline__ float ex2(float x) { return __builtin_amdgcn_exp2f(x); }
; __device__ __forceinline__ void phase_cmp(const Params& p, LAS unsigned char* lds, const bf16_t* Z, const float* G, const bf16_t* KC, const bf16_t* ACCW, float* ACC, int* IDX, ...
;     ...
;             for (int t = 0, bi = 0; t < nt; ++t, bi ^= 1) {
;                 const LAS bf16_t* Ks = Ks0 + bi * TLB;
; #pragma unroll
;                 for (int sub = 0; sub < 2; ++sub) {
;                     const int k0 = 64 * t + 32 * sub;
;                     if (16 * k0 + 31 > q0w + 31) continue;
;                     f32x16 s = qk_sub<4>(qf, Ks, 32 * sub, 0, r, h);
; #pragma unroll
;                     for (int g4 = 0; g4 < 4; ++g4) {
;                         float sum4 = 0.f, p3 = 0.f;
; #pragma unroll
;                         for (int e = 0; e < 4; ++e) { const int key = k0 + 8 * g4 + 4 * h + e; const float pv = (16 * key + 31 <= qpos) ? ex2(s[4 * g4 + e] - m) * invL : 0.f; sum4 += pv; if (e == 3) p3 = pv; }
;                         const int j = (k0 >> 2) + 2 * g4 + h;
;                         __hip_atomic_fetch_add((unsigned*)(PS + j * 64 + ql), (unsigned)(sum4 * 268435456.f + 0.5f), __ATOMIC_RELAXED, __HIP_MEMORY_SCOPE_WORKGROUP);
;                         if (j + 1 < 256) __hip_atomic_fetch_add((unsigned*)(PS + (j + 1) * 64 + ql), (unsigned)(p3 * 268435456.f + 0.5f), __ATOMIC_RELAXED, __HIP_MEMORY_SCOPE_WORKGROUP);
;                     }
.Lc2_fast1:
	v_or_b32_e32 v26, s18, v87
	s_nop 11
	v_sub_f32_e32 v2, v2, v104
	v_sub_f32_e32 v3, v3, v104
	v_sub_f32_e32 v4, v4, v104
	v_sub_f32_e32 v5, v5, v104
	v_exp_f32_e32 v2, v2
	v_exp_f32_e32 v3, v3
	v_exp_f32_e32 v4, v4
	v_exp_f32_e32 v5, v5
	v_mul_f32_e32 v2, v34, v2
	v_mul_f32_e32 v3, v34, v3
	v_mul_f32_e32 v4, v34, v4
	v_mul_f32_e32 v5, v34, v5
	v_add_f32_e32 v2, v3, v2
	v_add_f32_e32 v2, v4, v2
	v_add_f32_e32 v2, v5, v2
	v_fma_f32 v2, v2, s55, 0.5
	v_cvt_u32_f32_e32 v2, v2
	v_lshlrev_b32_e32 v28, 8, v26
	v_add_u32_e32 v28, v135, v28
	ds_add_u32 v28, v2 offset:40960
	v_fma_f32 v5, v5, s55, 0.5
	v_cvt_u32_f32_e32 v5, v5
	v_cmp_gt_u32_e32 vcc, s57, v26
	s_and_saveexec_b64 s[18:19], vcc
	ds_add_u32 v28, v5 offset:41216
	s_or_b64 exec, exec, s[18:19]
	v_sub_f32_e32 v6, v6, v104
	v_sub_f32_e32 v7, v7, v104
	v_sub_f32_e32 v8, v8, v104
	v_sub_f32_e32 v9, v9, v104
	v_exp_f32_e32 v6, v6
	v_exp_f32_e32 v7, v7
	v_exp_f32_e32 v8, v8
	v_exp_f32_e32 v9, v9
	v_mul_f32_e32 v6, v34, v6
	v_mul_f32_e32 v7, v34, v7
	v_mul_f32_e32 v8, v34, v8
	v_mul_f32_e32 v9, v34, v9
	v_add_f32_e32 v6, v7, v6
	v_add_f32_e32 v6, v8, v6
	v_add_f32_e32 v6, v9, v6
	v_fma_f32 v6, v6, s55, 0.5
	v_cvt_u32_f32_e32 v6, v6
	v_or_b32_e32 v29, 2, v26
	v_lshlrev_b32_e32 v28, 8, v29
	v_add_u32_e32 v28, v135, v28
	ds_add_u32 v28, v6 offset:40960
	v_fma_f32 v9, v9, s55, 0.5
	v_cvt_u32_f32_e32 v9, v9
	v_cmp_gt_u32_e32 vcc, s57, v29
	s_and_saveexec_b64 s[18:19], vcc
	ds_add_u32 v28, v9 offset:41216
	s_or_b64 exec, exec, s[18:19]
	v_sub_f32_e32 v10, v10, v104
	v_sub_f32_e32 v11, v11, v104
	v_sub_f32_e32 v12, v12, v104
	v_sub_f32_e32 v13, v13, v104
	v_exp_f32_e32 v10, v10
	v_exp_f32_e32 v11, v11
	v_exp_f32_e32 v12, v12
	v_exp_f32_e32 v13, v13
	v_mul_f32_e32 v10, v34, v10
	v_mul_f32_e32 v11, v34, v11
	v_mul_f32_e32 v12, v34, v12
	v_mul_f32_e32 v13, v34, v13
	v_add_f32_e32 v10, v11, v10
	v_add_f32_e32 v10, v12, v10
	v_add_f32_e32 v10, v13, v10
	v_fma_f32 v10, v10, s55, 0.5
	v_cvt_u32_f32_e32 v10, v10
	v_or_b32_e32 v29, 4, v26
	v_lshlrev_b32_e32 v28, 8, v29
	v_add_u32_e32 v28, v135, v28
	ds_add_u32 v28, v10 offset:40960
	v_fma_f32 v13, v13, s55, 0.5
	v_cvt_u32_f32_e32 v13, v13
	v_cmp_gt_u32_e32 vcc, s57, v29
	s_and_saveexec_b64 s[18:19], vcc
	ds_add_u32 v28, v13 offset:41216
	s_or_b64 exec, exec, s[18:19]
	v_sub_f32_e32 v14, v14, v104
	v_sub_f32_e32 v15, v15, v104
	v_sub_f32_e32 v16, v16, v104
	v_sub_f32_e32 v17, v17, v104
	v_exp_f32_e32 v14, v14
	v_exp_f32_e32 v15, v15
	v_exp_f32_e32 v16, v16
	v_exp_f32_e32 v17, v17
	v_mul_f32_e32 v14, v34, v14
	v_mul_f32_e32 v15, v34, v15
	v_mul_f32_e32 v16, v34, v16
	v_mul_f32_e32 v17, v34, v17
	v_add_f32_e32 v14, v15, v14
	v_add_f32_e32 v14, v16, v14
	v_add_f32_e32 v14, v17, v14
	v_fma_f32 v14, v14, s55, 0.5
	v_cvt_u32_f32_e32 v14, v14
	v_or_b32_e32 v29, 6, v26
	v_lshlrev_b32_e32 v28, 8, v29
	v_add_u32_e32 v28, v135, v28
	ds_add_u32 v28, v14 offset:40960
	v_fma_f32 v17, v17, s55, 0.5
	v_cvt_u32_f32_e32 v17, v17
	v_cmp_gt_u32_e32 vcc, s57, v29
	s_and_saveexec_b64 s[18:19], vcc
	ds_add_u32 v28, v17 offset:41216
	s_or_b64 exec, exec, s[18:19]
	s_branch .Lc2_after1
.LBB0_401:
	v_add_u32_e32 v27, v26, v122
	ds_read_b128 v[2:5], v27
	ds_read_b128 v[28:31], v27 offset:32
	ds_read_b128 v[152:155], v27 offset:64
	ds_read_b128 v[156:159], v27 offset:96
	s_lshr_b32 s18, s21, 2
	s_waitcnt lgkmcnt(3)
	v_mfma_f32_32x32x16_bf16 v[2:17], v[2:5], v[50:53], 0
	s_waitcnt lgkmcnt(2)
	v_mfma_f32_32x32x16_bf16 v[2:17], v[28:31], v[54:57], v[2:17]
	s_waitcnt lgkmcnt(1)
	v_mfma_f32_32x32x16_bf16 v[2:17], v[152:155], v[58:61], v[2:17]
	v_or_b32_e32 v27, s18, v87
	s_add_i32 s19, s20, 0x20f
	s_cmp_le_i32 s19, s41
	s_waitcnt lgkmcnt(0)
	v_mfma_f32_32x32x16_bf16 v[2:17], v[156:159], v[62:65], v[2:17]
	s_cbranch_scc1 .Lc2_fast0
	v_add_u32_e32 v28, 31, v0
	v_cmp_le_i32_e32 vcc, v28, v96
	v_add_u32_e32 v28, 47, v0
	s_nop 8
	v_sub_f32_e32 v2, v2, v104
	v_exp_f32_e32 v2, v2
	v_sub_f32_e32 v3, v3, v104
	v_exp_f32_e32 v3, v3
	v_sub_f32_e32 v4, v4, v104
	v_fma_f32 v2, v34, v2, 0
	v_exp_f32_e32 v4, v4
	v_cndmask_b32_e32 v2, 0, v2, vcc
	v_mul_f32_e32 v3, v34, v3
	v_cmp_le_i32_e32 vcc, v28, v96
	v_mul_f32_e32 v4, v34, v4
	s_nop 0
	v_cndmask_b32_e32 v3, 0, v3, vcc
	v_add_f32_e32 v2, v3, v2
	v_add_u32_e32 v3, 63, v0
	v_cmp_le_i32_e32 vcc, v3, v96
	s_nop 1
	v_cndmask_b32_e32 v3, 0, v4, vcc
	v_add_f32_e32 v3, v3, v2
	v_sub_f32_e32 v2, v5, v104
	v_exp_f32_e32 v2, v2
	v_cmp_le_i32_e32 vcc, v0, v95
	v_mul_f32_e32 v2, v34, v2
	s_nop 0
	v_cndmask_b32_e32 v2, 0, v2, vcc
	v_add_f32_e32 v4, v2, v3
	v_fma_f32 v4, v4, s55, 0.5
	v_cvt_u32_f32_e32 v4, v4
	v_lshlrev_b32_e32 v3, 8, v27
	v_add_u32_e32 v3, v135, v3
	v_cmp_gt_u32_e32 vcc, s57, v27
	ds_add_u32 v3, v4 offset:40960
	s_and_saveexec_b64 s[18:19], vcc
	s_cbranch_execz .LBB0_403
	v_fma_f32 v2, v2, s55, 0.5
	v_cvt_u32_f32_e32 v2, v2
	ds_add_u32 v3, v2 offset:41216

; __device__ __forceinline__ float ex2(float x) { return __builtin_amdgcn_exp2f(x); }
; __device__ __forceinline__ void phase_cmp(const Params& p, LAS unsigned char* lds, const bf16_t* Z, const float* G, const bf16_t* KC, const bf16_t* ACCW, float* ACC, int* IDX, ...
;     ...
;                 for (int sub = 0; sub < 2; ++sub) {
;                     const int k0 = 64 * t + 32 * sub;
;                     if (16 * k0 + 31 > q0w + 31) continue;
;                     f32x16 s = qk_sub<4>(qf, Ks, 32 * sub, 0, r, h);
; #pragma unroll
;                     for (int g4 = 0; g4 < 4; ++g4) {
;                         float sum4 = 0.f, p3 = 0.f;
; #pragma unroll
;                         for (int e = 0; e < 4; ++e) { const int key = k0 + 8 * g4 + 4 * h + e; const float pv = (16 * key + 31 <= qpos) ? ex2(s[4 * g4 + e] - m) * invL : 0.f; sum4 += pv; if (e == 3) p3 = pv; }
;                         const int j = (k0 >> 2) + 2 * g4 + h;
;                         __hip_atomic_fetch_add((unsigned*)(PS + j * 64 + ql), (unsigned)(sum4 * 268435456.f + 0.5f), __ATOMIC_RELAXED, __HIP_MEMORY_SCOPE_WORKGROUP);
;                         if (j + 1 < 256) __hip_atomic_fetch_add((unsigned*)(PS + (j + 1) * 64 + ql), (unsigned)(p3 * 268435456.f + 0.5f), __ATOMIC_RELAXED, __HIP_MEMORY_SCOPE_WORKGROUP);
;                     }
.LBB0_410:
	v_add_u32_e32 v30, v26, v125
	ds_read_b128 v[2:5], v30
	ds_read_b128 v[26:29], v30 offset:32
	ds_read_b128 v[152:155], v30 offset:64
	ds_read_b128 v[156:159], v30 offset:96
	s_add_i32 s18, s21, 32
	s_lshr_b32 s18, s18, 2
	s_waitcnt lgkmcnt(3)
	v_mfma_f32_32x32x16_bf16 v[2:17], v[2:5], v[50:53], 0
	s_waitcnt lgkmcnt(2)
	v_mfma_f32_32x32x16_bf16 v[2:17], v[26:29], v[54:57], v[2:17]
	s_waitcnt lgkmcnt(1)
	v_mfma_f32_32x32x16_bf16 v[2:17], v[152:155], v[58:61], v[2:17]
	s_add_i32 s19, s20, 0x40f
	s_cmp_le_i32 s19, s41
	s_waitcnt lgkmcnt(0)
	v_mfma_f32_32x32x16_bf16 v[2:17], v[156:159], v[62:65], v[2:17]
	s_cbranch_scc1 .Lc2_fast1
	v_add_u32_e32 v28, 0x21f, v0
	v_cmp_le_i32_e32 vcc, v28, v96
	v_add_u32_e32 v28, 0x22f, v0
	v_add_u32_e32 v27, 0x200, v0
	v_or_b32_e32 v26, s18, v87
	s_nop 6
	v_sub_f32_e32 v2, v2, v104
	v_exp_f32_e32 v2, v2
	v_sub_f32_e32 v3, v3, v104
	v_exp_f32_e32 v3, v3
	v_sub_f32_e32 v4, v4, v104
	v_fma_f32 v2, v34, v2, 0
	v_exp_f32_e32 v4, v4
	v_cndmask_b32_e32 v2, 0, v2, vcc
	v_mul_f32_e32 v3, v34, v3
	v_cmp_le_i32_e32 vcc, v28, v96
	v_mul_f32_e32 v4, v34, v4
	s_nop 0
	v_cndmask_b32_e32 v3, 0, v3, vcc
	v_add_f32_e32 v2, v3, v2
	v_add_u32_e32 v3, 0x23f, v0
	v_cmp_le_i32_e32 vcc, v3, v96
	s_nop 1
	v_cndmask_b32_e32 v3, 0, v4, vcc
	v_add_f32_e32 v3, v3, v2
	v_sub_f32_e32 v2, v5, v104
	v_exp_f32_e32 v2, v2
	v_cmp_le_i32_e32 vcc, v27, v95
	v_mul_f32_e32 v2, v34, v2
	s_nop 0
	v_cndmask_b32_e32 v2, 0, v2, vcc
	v_add_f32_e32 v4, v2, v3
	v_fma_f32 v4, v4, s55, 0.5
	v_cvt_u32_f32_e32 v4, v4
	v_lshlrev_b32_e32 v3, 8, v26
	v_add_u32_e32 v3, v135, v3
	v_cmp_gt_u32_e32 vcc, s57, v26
	ds_add_u32 v3, v4 offset:40960
	s_and_saveexec_b64 s[18:19], vcc
	s_cbranch_execz .LBB0_412
	v_fma_f32 v2, v2, s55, 0.5
	v_cvt_u32_f32_e32 v2, v2
	ds_add_u32 v3, v2 offset:41216

; #define TL_NEXT(Kg, kpitch, Vg, vpitch, t, t1, bi) do { if ((t) + 1 < (t1)) { TL_WRITE((bi) ^ 1); if ((t) + 2 < (t1)) TL_FETCH(Kg, kpitch, Vg, vpitch, (t) + 2); } __syncthreads(); } while (0)
; __device__ __forceinline__ void phase_cmp(const Params& p, LAS unsigned char* lds, const bf16_t* Z, const float* G, const bf16_t* KC, const bf16_t* ACCW, float* ACC, int* IDX, ...
;     ...
;                 TL_NEXT(Kg, 64, Vg, 64, t, nt, bi);
;             }
.LBB0_418:
	s_or_b64 exec, exec, s[18:19]
.Lc2_after1:
	s_add_i32 s18, s23, 1
	s_xor_b32 s22, s22, 1
	s_cmp_ge_u32 s18, s17
	s_cbranch_scc1 .LBB0_397
.LBB0_419:
	s_mul_i32 s19, s22, 0x4800
	s_add_i32 s19, s19, 0
	v_add3_u32 v0, s19, v105, v98
	s_waitcnt vmcnt(1)
	ds_write_b128 v0, v[18:21]
	v_lshl_add_u32 v0, v118, 1, s19
	s_add_i32 s19, s23, 2
	s_cmp_ge_u32 s19, s17
	s_waitcnt vmcnt(0)
	ds_write_b16 v0, v22 offset:9216
	ds_write_b16_d16_hi v0, v22 offset:9360
	ds_write_b16 v0, v23 offset:9504
	ds_write_b16_d16_hi v0, v23 offset:9648
	ds_write_b16 v0, v24 offset:9792
	ds_write_b16_d16_hi v0, v24 offset:9936
	ds_write_b16 v0, v25 offset:10080
	ds_write_b16_d16_hi v0, v25 offset:10224
	s_cbranch_scc1 .LBB0_397
	v_add_u32_e32 v2, s21, v136
	v_ashrrev_i32_e32 v3, 31, v2
	v_lshlrev_b64 v[2:3], 7, v[2:3]
	v_add_u32_e32 v0, s21, v129
	v_lshl_add_u64 v[2:3], v[100:101], 0, v[2:3]
	v_lshlrev_b64 v[4:5], 7, v[0:1]
	v_lshl_add_u64 v[4:5], v[102:103], 0, v[4:5]
	global_load_dwordx4 v[18:21], v[2:3], off
	global_load_dwordx4 v[22:25], v[4:5], off
	s_branch .LBB0_397

; __device__ __forceinline__ void phase_cmp(const Params& p, LAS unsigned char* lds, const bf16_t* Z, const float* G, const bf16_t* KC, const bf16_t* ACCW, float* ACC, int* IDX, ...
;     ...
;                 for (int i = 0; i < 4; ++i) { const int j = lane + 64 * i; ok[i] = (j >= 1) && (j <= cur - 2); v[i] = ok[i] ? PS[j * 64 + qi] : 0u; }
;                 unsigned T = 0u;
;     ...
; #pragma unroll
;                     for (int i = 0; i < 4; ++i) cnt += __builtin_popcountll(__ballot(ok[i] && v[i] >= trial));
;                     if (cnt >= 13) T = trial; }
.LBB0_433:
	s_lshl_b32 s20, 1, s22
	s_or_b32 s23, s20, s96
	s_waitcnt lgkmcnt(0)
	v_cmp_le_u32_e64 s[20:21], s23, v2
	v_cmp_le_u32_e64 s[98:99], s23, v5
	v_cmp_le_u32_e64 s[100:101], s23, v4
	s_bcnt1_i32_b64 s24, s[20:21]
	v_cmp_le_u32_e64 s[20:21], s23, v0
	s_bcnt1_i32_b64 s25, s[98:99]
	s_add_i32 s24, s24, s25
	s_bcnt1_i32_b64 s25, s[100:101]
	s_add_i32 s24, s24, s25
	s_bcnt1_i32_b64 s25, s[20:21]
	s_add_i32 s24, s24, s25
	s_cmp_gt_u32 s24, 12
	s_cselect_b32 s96, s23, s96
	s_add_i32 s22, s22, -1
	s_cmp_eq_u32 s22, -1
	s_cbranch_scc0 .LBB0_433
	v_cmp_lt_u32_e64 s[20:21], s96, v2
	s_and_b64 s[80:81], s[70:71], s[20:21]
	v_cmp_lt_u32_e64 s[20:21], s96, v5
	s_and_b64 s[78:79], vcc, s[20:21]
	v_cmp_lt_u32_e64 s[20:21], s96, v4
	s_and_b64 s[76:77], s[16:17], s[20:21]
	v_cmp_lt_u32_e64 s[20:21], s96, v0
	s_and_b64 s[74:75], s[18:19], s[20:21]
	s_ashr_i32 s21, s95, 31
	s_add_u32 s20, s95, s26
	s_addc_u32 s21, s21, 0
	s_lshl_b64 s[20:21], s[20:21], 7
	v_cndmask_b32_e64 v3, 0, 1, s[80:81]
	v_cndmask_b32_e64 v8, 0, 1, s[78:79]
	v_cndmask_b32_e64 v7, 0, 1, s[76:77]
	v_cndmask_b32_e64 v6, 0, 1, s[74:75]
	s_add_u32 s72, s92, s20
	v_cmp_ne_u32_e64 s[22:23], 0, v3
	v_cmp_ne_u32_e64 s[24:25], 0, v8
	v_cmp_ne_u32_e64 s[38:39], 0, v7
	v_cmp_ne_u32_e64 s[40:41], 0, v6
	s_addc_u32 s73, s93, s21
	s_and_saveexec_b64 s[20:21], s[8:9]
	s_cbranch_execz .LBB0_436
	v_mov_b32_e32 v11, s94
	v_mov_b32_e32 v12, s91
	v_mov_b32_e32 v10, v1
	global_store_dwordx3 v1, v[10:12], s[72:73]
